# write-through (sc1) state stores in the HGRN2 and DeltaNet chunk scans: less dirty L2 for the P3|P4 barrier leader's write-back
# baseline (speedup 1.0000x reference)
; #define GAS __attribute__((address_space(1)))
; __device__ __forceinline__ unsigned pk2(float lo, float hi) { const f32x2_t v = {lo, hi}; return __builtin_bit_cast(unsigned, __builtin_convertvector(v, bf16x2_t)); }
; __device__ __forceinline__ void p3_hg_scan(int job, bf16_t* HGR, const float* dec, int tid, const bool ST = true) {
;     ...
;     for (int n0 = 0; n0 < NCH; n0 += 6) {
; #pragma unroll
;         for (int u = 0; u < 6; ++u) { const int n = n0 + u; if (n < NCH) { const int unit = (b * NCH + n) * 4 + h;
;             const v4u bv = bn[u]; const f32x4 dva = da[u], dvb = db[u];
;             const int nn = (n + 6 < NCH) ? n + 6 : NCH - 1; const int unit2 = (b * NCH + nn) * 4 + h;
;             bn[u] = *(const GAS v4u*)(HGR + (size_t)unit2 * 32768 + eoff); da[u] = *(const GAS f32x4*)(dec + (size_t)unit2 * 128 + koff); db[u] = *(const GAS f32x4*)(dec + (size_t)unit2 * 128 + koff + 16);
;             f32x4 b0, b1; unpack8(bv, b0, b1);
;             const f32x4 Sn0 = S0 * dva + b0, Sn1 = S1 * dvb + b1;
;             asm volatile("" :: "v"(Sn0[0]), "v"(Sn0[1]), "v"(Sn0[2]), "v"(Sn0[3]), "v"(Sn1[0]), "v"(Sn1[1]), "v"(Sn1[2]), "v"(Sn1[3]) : "memory");
;             if (ST) *(GAS v4u*)(HGR + (size_t)unit * 32768 + eoff) = (v4u){pk2(S0[0], S0[1]), pk2(S0[2], S0[3]), pk2(S1[0], S1[1]), pk2(S1[2], S1[3])};
;             S0 = Sn0; S1 = Sn1; } }
.LBB0_665:
	s_add_i32 s9, s8, -5
	s_min_u32 s0, s9, 0x79
	s_add_i32 s0, s0, s4
	s_lshl_b32 s0, s0, 2
	s_waitcnt vmcnt(1)
	v_mov_b64_e32 v[88:89], v[64:65]
	s_or_b32 s0, s0, s3
	v_mov_b64_e32 v[86:87], v[62:63]
	v_mov_b64_e32 v[64:65], v[4:5]
	s_lshl_b64 s[10:11], s[0:1], 16
	v_mov_b32_e32 v1, v69
	v_mov_b32_e32 v102, v68
	v_mov_b32_e32 v103, v67
	v_mov_b32_e32 v104, v66
	v_mov_b64_e32 v[68:69], v[12:13]
	v_mov_b64_e32 v[62:63], v[2:3]
	v_lshl_add_u64 v[2:3], v[82:83], 0, s[10:11]
	s_lshl_b64 s[10:11], s[0:1], 9
	s_sub_i32 s0, s6, 20
	v_mov_b64_e32 v[66:67], v[10:11]
	v_lshl_add_u64 v[10:11], v[84:85], 0, s[10:11]
	s_lshl_b64 s[10:11], s[0:1], 16
	s_add_i32 s0, s8, -4
	s_min_u32 s0, s0, 0x79
	s_add_i32 s0, s0, s4
	v_mov_b32_e32 v94, v7
	v_mov_b32_e32 v96, v6
	v_mov_b64_e32 v[92:93], v[56:57]
	s_lshl_b32 s0, s0, 2
	v_mov_b32_e32 v97, v9
	v_mov_b32_e32 v95, v8
	v_mov_b64_e32 v[90:91], v[54:55]
	v_lshlrev_b32_e32 v54, 16, v96
	v_and_b32_e32 v55, 0xffff0000, v96
	v_lshlrev_b32_e32 v56, 16, v94
	v_and_b32_e32 v57, 0xffff0000, v94
	s_or_b32 s0, s0, s3
	v_lshlrev_b32_e32 v94, 16, v95
	v_and_b32_e32 v95, 0xffff0000, v95
	v_lshlrev_b32_e32 v96, 16, v97
	v_and_b32_e32 v97, 0xffff0000, v97
	v_pk_fma_f32 v[98:99], v[64:65], v[48:49], v[56:57]
	v_pk_fma_f32 v[100:101], v[62:63], v[46:47], v[54:55]
	v_cvt_pk_bf16_f32 v46, v46, v47
	v_cvt_pk_bf16_f32 v47, v48, v49
	v_cvt_pk_bf16_f32 v48, v78, v79
	v_cvt_pk_bf16_f32 v49, v80, v81
	v_lshl_add_u64 v[54:55], v[82:83], 0, s[10:11]
	s_lshl_b64 s[10:11], s[0:1], 16
	global_load_dwordx4 v[6:9], v[2:3], off nt
	s_nop 0
	global_load_dwordx4 v[2:5], v[10:11], off nt
	s_nop 0
	global_load_dwordx4 v[10:13], v[10:11], off offset:64 nt
	v_pk_fma_f32 v[96:97], v[68:69], v[80:81], v[96:97]
	v_pk_fma_f32 v[94:95], v[66:67], v[78:79], v[94:95]
	v_lshlrev_b32_e32 v78, 16, v102
	global_store_dwordx4 v[54:55], v[46:49], off sc1
	v_and_b32_e32 v79, 0xffff0000, v102
	v_lshlrev_b32_e32 v80, 16, v1
	v_lshl_add_u64 v[46:47], v[82:83], 0, s[10:11]
	s_lshl_b64 s[10:11], s[0:1], 9
	v_lshl_add_u64 v[48:49], v[84:85], 0, s[10:11]
	global_load_dwordx4 v[66:69], v[46:47], off nt
	global_load_dwordx4 v[54:57], v[48:49], off nt
	global_load_dwordx4 v[62:65], v[48:49], off offset:64 nt
	v_lshlrev_b32_e32 v46, 16, v104
	v_and_b32_e32 v47, 0xffff0000, v104
	v_lshlrev_b32_e32 v48, 16, v103
	v_and_b32_e32 v49, 0xffff0000, v103
	v_and_b32_e32 v81, 0xffff0000, v1
	v_pk_fma_f32 v[48:49], v[92:93], v[98:99], v[48:49]
	v_pk_fma_f32 v[46:47], v[90:91], v[100:101], v[46:47]
	v_pk_fma_f32 v[80:81], v[88:89], v[96:97], v[80:81]
	v_pk_fma_f32 v[78:79], v[86:87], v[94:95], v[78:79]
	s_add_i32 s0, s6, -16
	s_lshl_b64 s[10:11], s[0:1], 16
	v_cvt_pk_bf16_f32 v86, v100, v101
	v_cvt_pk_bf16_f32 v87, v98, v99
	v_cvt_pk_bf16_f32 v88, v94, v95
	v_cvt_pk_bf16_f32 v89, v96, v97
	v_lshl_add_u64 v[90:91], v[82:83], 0, s[10:11]
	s_cmpk_gt_u32 s9, 0x7d
	global_store_dwordx4 v[90:91], v[86:89], off sc1
	s_cbranch_scc1 .LBB0_669
	s_add_i32 s0, s8, -3
	s_min_u32 s0, s0, 0x79
	s_add_i32 s0, s0, s4
	s_lshl_b32 s0, s0, 2
	s_or_b32 s0, s0, s3
	s_lshl_b64 s[10:11], s[0:1], 16
	v_lshl_add_u64 v[94:95], v[82:83], 0, s[10:11]
	s_lshl_b64 s[10:11], s[0:1], 9
	v_lshl_add_u64 v[90:91], v[84:85], 0, s[10:11]
	global_load_dwordx4 v[86:89], v[90:91], off nt
	s_nop 0
	global_load_dwordx4 v[90:93], v[90:91], off offset:64 nt
	s_nop 0
	global_load_dwordx4 v[94:97], v[94:95], off nt
	s_waitcnt vmcnt(22)
	v_lshlrev_b32_e32 v100, 16, v59
	v_and_b32_e32 v101, 0xffff0000, v59
	v_lshlrev_b32_e32 v98, 16, v58
	v_and_b32_e32 v99, 0xffff0000, v58
	v_lshlrev_b32_e32 v104, 16, v61
	v_and_b32_e32 v105, 0xffff0000, v61
	s_waitcnt vmcnt(21)
	v_pk_fma_f32 v[16:17], v[16:17], v[48:49], v[100:101]
	s_add_i32 s0, s6, -12
	v_lshlrev_b32_e32 v102, 16, v60
	v_and_b32_e32 v103, 0xffff0000, v60
	v_cvt_pk_bf16_f32 v58, v46, v47
	v_cvt_pk_bf16_f32 v59, v48, v49
	v_pk_fma_f32 v[14:15], v[14:15], v[46:47], v[98:99]
	s_waitcnt vmcnt(20)
	v_pk_fma_f32 v[28:29], v[28:29], v[80:81], v[104:105]
	v_mov_b64_e32 v[48:49], v[16:17]
	s_lshl_b64 s[10:11], s[0:1], 16
	v_cvt_pk_bf16_f32 v60, v78, v79
	v_cvt_pk_bf16_f32 v61, v80, v81
	v_pk_fma_f32 v[26:27], v[26:27], v[78:79], v[102:103]
	v_mov_b64_e32 v[46:47], v[14:15]
	v_mov_b64_e32 v[80:81], v[28:29]
	v_lshl_add_u64 v[14:15], v[82:83], 0, s[10:11]
	v_mov_b64_e32 v[78:79], v[26:27]
	global_store_dwordx4 v[14:15], v[58:61], off sc1
	s_waitcnt vmcnt(3)
	v_mov_b64_e32 v[14:15], v[86:87]
	s_waitcnt vmcnt(2)
	v_mov_b64_e32 v[26:27], v[90:91]
	v_mov_b64_e32 v[16:17], v[88:89]
	v_mov_b64_e32 v[28:29], v[92:93]
	s_waitcnt vmcnt(1)
	v_mov_b32_e32 v58, v94
	v_mov_b32_e32 v59, v95
	v_mov_b32_e32 v60, v96
	v_mov_b32_e32 v61, v97
	s_cmpk_gt_u32 s9, 0x7c
	s_cbranch_scc0 .LBB0_670

; #define GAS __attribute__((address_space(1)))
; __device__ __forceinline__ unsigned pk2(float lo, float hi) { const f32x2_t v = {lo, hi}; return __builtin_bit_cast(unsigned, __builtin_convertvector(v, bf16x2_t)); }
; __device__ __forceinline__ void p3_hg_scan(int job, bf16_t* HGR, const float* dec, int tid, const bool ST = true) {
;     ...
;     for (int n0 = 0; n0 < NCH; n0 += 6) {
; #pragma unroll
;         for (int u = 0; u < 6; ++u) { const int n = n0 + u; if (n < NCH) { const int unit = (b * NCH + n) * 4 + h;
;             const v4u bv = bn[u]; const f32x4 dva = da[u], dvb = db[u];
;             const int nn = (n + 6 < NCH) ? n + 6 : NCH - 1; const int unit2 = (b * NCH + nn) * 4 + h;
;             bn[u] = *(const GAS v4u*)(HGR + (size_t)unit2 * 32768 + eoff); da[u] = *(const GAS f32x4*)(dec + (size_t)unit2 * 128 + koff); db[u] = *(const GAS f32x4*)(dec + (size_t)unit2 * 128 + koff + 16);
;             f32x4 b0, b1; unpack8(bv, b0, b1);
;             const f32x4 Sn0 = S0 * dva + b0, Sn1 = S1 * dvb + b1;
;             asm volatile("" :: "v"(Sn0[0]), "v"(Sn0[1]), "v"(Sn0[2]), "v"(Sn0[3]), "v"(Sn1[0]), "v"(Sn1[1]), "v"(Sn1[2]), "v"(Sn1[3]) : "memory");
;             if (ST) *(GAS v4u*)(HGR + (size_t)unit * 32768 + eoff) = (v4u){pk2(S0[0], S0[1]), pk2(S0[2], S0[3]), pk2(S1[0], S1[1]), pk2(S1[2], S1[3])};
;             S0 = Sn0; S1 = Sn1; } }
.LBB0_668:
	s_add_i32 s0, s8, -1
	s_min_u32 s0, s0, 0x79
	s_add_i32 s0, s0, s4
	s_lshl_b32 s0, s0, 2
	s_or_b32 s0, s0, s3
	s_lshl_b64 s[10:11], s[0:1], 16
	v_lshl_add_u64 v[94:95], v[82:83], 0, s[10:11]
	s_lshl_b64 s[10:11], s[0:1], 9
	v_lshl_add_u64 v[90:91], v[84:85], 0, s[10:11]
	global_load_dwordx4 v[86:89], v[90:91], off nt
	s_nop 0
	global_load_dwordx4 v[90:93], v[90:91], off offset:64 nt
	s_nop 0
	global_load_dwordx4 v[94:97], v[94:95], off nt
	s_waitcnt vmcnt(16)
	v_lshlrev_b32_e32 v100, 16, v71
	v_and_b32_e32 v101, 0xffff0000, v71
	v_lshlrev_b32_e32 v98, 16, v70
	v_and_b32_e32 v99, 0xffff0000, v70
	v_lshlrev_b32_e32 v104, 16, v73
	v_and_b32_e32 v105, 0xffff0000, v73
	s_waitcnt vmcnt(15)
	v_pk_fma_f32 v[32:33], v[32:33], v[48:49], v[100:101]
	s_add_i32 s0, s6, -4
	v_lshlrev_b32_e32 v102, 16, v72
	v_and_b32_e32 v103, 0xffff0000, v72
	v_cvt_pk_bf16_f32 v70, v46, v47
	v_cvt_pk_bf16_f32 v71, v48, v49
	v_pk_fma_f32 v[30:31], v[30:31], v[46:47], v[98:99]
	s_waitcnt vmcnt(14)
	v_pk_fma_f32 v[44:45], v[44:45], v[80:81], v[104:105]
	v_mov_b64_e32 v[48:49], v[32:33]
	s_lshl_b64 s[10:11], s[0:1], 16
	v_cvt_pk_bf16_f32 v72, v78, v79
	v_cvt_pk_bf16_f32 v73, v80, v81
	v_pk_fma_f32 v[42:43], v[42:43], v[78:79], v[102:103]
	v_mov_b64_e32 v[46:47], v[30:31]
	v_mov_b64_e32 v[80:81], v[44:45]
	v_lshl_add_u64 v[30:31], v[82:83], 0, s[10:11]
	v_mov_b64_e32 v[78:79], v[42:43]
	global_store_dwordx4 v[30:31], v[70:73], off sc1
	s_waitcnt vmcnt(3)
	v_mov_b64_e32 v[30:31], v[86:87]
	s_waitcnt vmcnt(2)
	v_mov_b64_e32 v[42:43], v[90:91]
	v_mov_b64_e32 v[32:33], v[88:89]
	v_mov_b64_e32 v[44:45], v[92:93]
	s_waitcnt vmcnt(1)
	v_mov_b32_e32 v70, v94
	v_mov_b32_e32 v71, v95
	v_mov_b32_e32 v72, v96
	v_mov_b32_e32 v73, v97
	s_cmpk_gt_u32 s9, 0x7a
	s_cbranch_scc1 .LBB0_664
	s_branch .LBB0_672

; #define GAS __attribute__((address_space(1)))
; __device__ __forceinline__ unsigned pk2(float lo, float hi) { const f32x2_t v = {lo, hi}; return __builtin_bit_cast(unsigned, __builtin_convertvector(v, bf16x2_t)); }
; __device__ __forceinline__ void p3_hg_scan(int job, bf16_t* HGR, const float* dec, int tid, const bool ST = true) {
;     ...
;     for (int n0 = 0; n0 < NCH; n0 += 6) {
; #pragma unroll
;         for (int u = 0; u < 6; ++u) { const int n = n0 + u; if (n < NCH) { const int unit = (b * NCH + n) * 4 + h;
;             const v4u bv = bn[u]; const f32x4 dva = da[u], dvb = db[u];
;             const int nn = (n + 6 < NCH) ? n + 6 : NCH - 1; const int unit2 = (b * NCH + nn) * 4 + h;
;             bn[u] = *(const GAS v4u*)(HGR + (size_t)unit2 * 32768 + eoff); da[u] = *(const GAS f32x4*)(dec + (size_t)unit2 * 128 + koff); db[u] = *(const GAS f32x4*)(dec + (size_t)unit2 * 128 + koff + 16);
;             f32x4 b0, b1; unpack8(bv, b0, b1);
;             const f32x4 Sn0 = S0 * dva + b0, Sn1 = S1 * dvb + b1;
;             asm volatile("" :: "v"(Sn0[0]), "v"(Sn0[1]), "v"(Sn0[2]), "v"(Sn0[3]), "v"(Sn1[0]), "v"(Sn1[1]), "v"(Sn1[2]), "v"(Sn1[3]) : "memory");
;             if (ST) *(GAS v4u*)(HGR + (size_t)unit * 32768 + eoff) = (v4u){pk2(S0[0], S0[1]), pk2(S0[2], S0[3]), pk2(S1[0], S1[1]), pk2(S1[2], S1[3])};
;             S0 = Sn0; S1 = Sn1; } }
.LBB0_670:
	s_add_i32 s0, s8, -2
	s_min_u32 s0, s0, 0x79
	s_add_i32 s0, s0, s4
	s_lshl_b32 s0, s0, 2
	s_or_b32 s0, s0, s3
	s_lshl_b64 s[10:11], s[0:1], 16
	v_lshl_add_u64 v[94:95], v[82:83], 0, s[10:11]
	s_lshl_b64 s[10:11], s[0:1], 9
	v_lshl_add_u64 v[90:91], v[84:85], 0, s[10:11]
	global_load_dwordx4 v[86:89], v[90:91], off nt
	s_nop 0
	global_load_dwordx4 v[90:93], v[90:91], off offset:64 nt
	s_nop 0
	global_load_dwordx4 v[94:97], v[94:95], off nt
	s_waitcnt vmcnt(19)
	v_lshlrev_b32_e32 v100, 16, v51
	v_and_b32_e32 v101, 0xffff0000, v51
	v_lshlrev_b32_e32 v98, 16, v50
	v_and_b32_e32 v99, 0xffff0000, v50
	v_lshlrev_b32_e32 v104, 16, v53
	v_and_b32_e32 v105, 0xffff0000, v53
	s_waitcnt vmcnt(18)
	v_pk_fma_f32 v[20:21], v[20:21], v[48:49], v[100:101]
	s_add_i32 s0, s6, -8
	v_lshlrev_b32_e32 v102, 16, v52
	v_and_b32_e32 v103, 0xffff0000, v52
	v_cvt_pk_bf16_f32 v50, v46, v47
	v_cvt_pk_bf16_f32 v51, v48, v49
	v_pk_fma_f32 v[18:19], v[18:19], v[46:47], v[98:99]
	s_waitcnt vmcnt(17)
	v_pk_fma_f32 v[24:25], v[24:25], v[80:81], v[104:105]
	v_mov_b64_e32 v[48:49], v[20:21]
	s_lshl_b64 s[10:11], s[0:1], 16
	v_cvt_pk_bf16_f32 v52, v78, v79
	v_cvt_pk_bf16_f32 v53, v80, v81
	v_pk_fma_f32 v[22:23], v[22:23], v[78:79], v[102:103]
	v_mov_b64_e32 v[46:47], v[18:19]
	v_mov_b64_e32 v[80:81], v[24:25]
	v_lshl_add_u64 v[18:19], v[82:83], 0, s[10:11]
	v_mov_b64_e32 v[78:79], v[22:23]
	global_store_dwordx4 v[18:19], v[50:53], off sc1
	s_waitcnt vmcnt(3)
	v_mov_b64_e32 v[18:19], v[86:87]
	s_waitcnt vmcnt(2)
	v_mov_b64_e32 v[22:23], v[90:91]
	v_mov_b64_e32 v[20:21], v[88:89]
	v_mov_b64_e32 v[24:25], v[92:93]
	s_waitcnt vmcnt(1)
	v_mov_b32_e32 v50, v94
	v_mov_b32_e32 v51, v95
	v_mov_b32_e32 v52, v96
	v_mov_b32_e32 v53, v97
	s_cmpk_gt_u32 s9, 0x7b
	s_cbranch_scc0 .LBB0_668

; #define GAS __attribute__((address_space(1)))
; __device__ __forceinline__ unsigned pk2(float lo, float hi) { const f32x2_t v = {lo, hi}; return __builtin_bit_cast(unsigned, __builtin_convertvector(v, bf16x2_t)); }
; __device__ __forceinline__ void p3_hg_scan(int job, bf16_t* HGR, const float* dec, int tid, const bool ST = true) {
;     ...
;     for (int n0 = 0; n0 < NCH; n0 += 6) {
; #pragma unroll
;         for (int u = 0; u < 6; ++u) { const int n = n0 + u; if (n < NCH) { const int unit = (b * NCH + n) * 4 + h;
;             const v4u bv = bn[u]; const f32x4 dva = da[u], dvb = db[u];
;             const int nn = (n + 6 < NCH) ? n + 6 : NCH - 1; const int unit2 = (b * NCH + nn) * 4 + h;
;             bn[u] = *(const GAS v4u*)(HGR + (size_t)unit2 * 32768 + eoff); da[u] = *(const GAS f32x4*)(dec + (size_t)unit2 * 128 + koff); db[u] = *(const GAS f32x4*)(dec + (size_t)unit2 * 128 + koff + 16);
;             f32x4 b0, b1; unpack8(bv, b0, b1);
;             const f32x4 Sn0 = S0 * dva + b0, Sn1 = S1 * dvb + b1;
;             asm volatile("" :: "v"(Sn0[0]), "v"(Sn0[1]), "v"(Sn0[2]), "v"(Sn0[3]), "v"(Sn1[0]), "v"(Sn1[1]), "v"(Sn1[2]), "v"(Sn1[3]) : "memory");
;             if (ST) *(GAS v4u*)(HGR + (size_t)unit * 32768 + eoff) = (v4u){pk2(S0[0], S0[1]), pk2(S0[2], S0[3]), pk2(S1[0], S1[1]), pk2(S1[2], S1[3])};
;             S0 = Sn0; S1 = Sn1; } }
.LBB0_672:
	s_min_u32 s0, s8, 0x79
	s_add_i32 s0, s0, s4
	s_lshl_b32 s0, s0, 2
	s_or_b32 s0, s0, s3
	s_lshl_b64 s[10:11], s[0:1], 16
	v_lshl_add_u64 v[94:95], v[82:83], 0, s[10:11]
	s_lshl_b64 s[10:11], s[0:1], 9
	v_lshl_add_u64 v[90:91], v[84:85], 0, s[10:11]
	global_load_dwordx4 v[86:89], v[90:91], off nt
	s_nop 0
	global_load_dwordx4 v[90:93], v[90:91], off offset:64 nt
	s_nop 0
	global_load_dwordx4 v[94:97], v[94:95], off nt
	s_waitcnt vmcnt(13)
	v_lshlrev_b32_e32 v100, 16, v75
	v_and_b32_e32 v101, 0xffff0000, v75
	v_lshlrev_b32_e32 v104, 16, v77
	v_and_b32_e32 v105, 0xffff0000, v77
	v_lshlrev_b32_e32 v98, 16, v74
	v_and_b32_e32 v99, 0xffff0000, v74
	v_lshlrev_b32_e32 v102, 16, v76
	v_and_b32_e32 v103, 0xffff0000, v76
	s_mov_b32 s7, s1
	s_waitcnt vmcnt(12)
	v_pk_fma_f32 v[36:37], v[36:37], v[48:49], v[100:101]
	s_waitcnt vmcnt(11)
	v_pk_fma_f32 v[40:41], v[40:41], v[80:81], v[104:105]
	v_cvt_pk_bf16_f32 v74, v46, v47
	v_cvt_pk_bf16_f32 v75, v48, v49
	v_cvt_pk_bf16_f32 v76, v78, v79
	v_cvt_pk_bf16_f32 v77, v80, v81
	v_pk_fma_f32 v[34:35], v[34:35], v[46:47], v[98:99]
	v_pk_fma_f32 v[38:39], v[38:39], v[78:79], v[102:103]
	s_lshl_b64 s[10:11], s[6:7], 16
	v_mov_b64_e32 v[80:81], v[40:41]
	v_mov_b64_e32 v[48:49], v[36:37]
	v_lshl_add_u64 v[98:99], v[82:83], 0, s[10:11]
	v_mov_b64_e32 v[78:79], v[38:39]
	v_mov_b64_e32 v[46:47], v[34:35]
	global_store_dwordx4 v[98:99], v[74:77], off sc1
	s_waitcnt vmcnt(3)
	v_mov_b64_e32 v[34:35], v[86:87]
	s_waitcnt vmcnt(2)
	v_mov_b64_e32 v[38:39], v[90:91]
	v_mov_b64_e32 v[36:37], v[88:89]
	v_mov_b64_e32 v[40:41], v[92:93]
	s_waitcnt vmcnt(1)
	v_mov_b32_e32 v74, v94
	v_mov_b32_e32 v75, v95
	v_mov_b32_e32 v76, v96
	v_mov_b32_e32 v77, v97
	s_branch .LBB0_664
.LBB0_673:
	s_and_b64 vcc, exec, s[0:1]
	s_cbranch_vccz .LBB0_840
	s_lshl_b32 s0, s2, 2
	s_and_b32 s4, s0, 28
	s_add_u32 s33, s60, 0x200000
	s_addc_u32 s36, s61, 0
	s_lshl_b32 s0, s2, 5
	s_and_b32 s29, s0, 0x80
	s_and_b32 s5, s2, 3
	s_lshl_b32 s19, s29, 2
	s_or_b32 s28, s5, s19
	s_and_b32 s18, s2, 7
	s_lshl_b32 s0, s28, 16
	s_add_u32 s6, s62, s0
	s_addc_u32 s7, s63, 0
	s_lshl_b32 s0, s28, 15
	s_add_u32 s8, s64, s0
	s_addc_u32 s9, s65, 0
	s_lshl_b32 s0, s48, 5
	v_lshl_or_b32 v98, s48, 8, v234
	v_mov_b32_e32 v99, 0
	s_lshl_b32 s11, s73, 9
	s_and_b32 s3, s0, 0x7fffffc0
	v_lshlrev_b64 v[108:109], 4, v[98:99]
	s_add_i32 s0, s3, s11
	s_waitcnt vmcnt(6)
	v_lshl_add_u64 v[2:3], s[6:7], 0, v[108:109]
	s_mov_b64 s[6:7], 0x4000
	v_or_b32_e32 v4, s0, v234
	s_bfe_u32 s35, s66, 0x10006
	v_lshl_add_u64 v[2:3], v[2:3], 0, s[6:7]
	v_ashrrev_i32_e32 v5, 31, v4
	s_lshl_b32 s0, s35, 3
	s_lshl_b32 s10, s28, 9
	s_waitcnt vmcnt(4)
	global_load_dwordx4 v[18:21], v[2:3], off
	v_lshlrev_b64 v[106:107], 4, v[4:5]
	s_add_u32 s38, s33, s10
	global_load_dwordx4 v[22:25], v[2:3], off offset:1024
	s_mov_b32 s1, 0
	v_lshl_add_u64 v[4:5], s[8:9], 0, v[106:107]
	s_addc_u32 s39, s36, 0
	global_load_dwordx4 v[10:13], v[2:3], off offset:2048
	s_or_b32 s10, s28, 4
	v_lshl_add_u64 v[6:7], v[4:5], 0, s[0:1]
	s_mov_b64 s[8:9], 0x1000
	global_load_dwordx4 v[2:5], v[2:3], off offset:3072
	s_lshl_b32 s37, s10, 16
	v_lshl_add_u64 v[8:9], v[6:7], 0, s[8:9]
	global_load_dwordx2 v[124:125], v[6:7], off
	v_mov_b64_e32 v[6:7], s[38:39]
	s_add_u32 s38, s62, s37
	global_load_dwordx2 v[142:143], v[8:9], off
	s_addc_u32 s39, s63, 0
	s_lshl_b32 s37, s10, 15
	global_load_dword v113, v[6:7], off
	v_lshl_add_u64 v[6:7], s[38:39], 0, v[108:109]
	s_add_u32 s38, s64, s37
	v_lshl_add_u64 v[6:7], v[6:7], 0, s[6:7]
	s_addc_u32 s39, s65, 0
	s_lshl_b32 s10, s10, 9
	global_load_dwordx4 v[62:65], v[6:7], off
	v_lshl_add_u64 v[8:9], s[38:39], 0, v[106:107]
	s_add_u32 s38, s33, s10
	global_load_dwordx4 v[58:61], v[6:7], off offset:1024
	s_addc_u32 s39, s36, 0
	global_load_dwordx4 v[14:17], v[6:7], off offset:2048
	s_or_b32 s10, s28, 8
	v_lshl_add_u64 v[26:27], v[8:9], 0, s[0:1]
	global_load_dwordx4 v[6:9], v[6:7], off offset:3072
	s_lshl_b32 s37, s10, 16
	v_lshl_add_u64 v[28:29], v[26:27], 0, s[8:9]
	global_load_dwordx2 v[140:141], v[26:27], off
	v_mov_b64_e32 v[26:27], s[38:39]
	s_add_u32 s38, s62, s37
	global_load_dwordx2 v[136:137], v[28:29], off
	s_addc_u32 s39, s63, 0
	s_lshl_b32 s37, s10, 15
	global_load_dword v138, v[26:27], off
	v_lshl_add_u64 v[26:27], s[38:39], 0, v[108:109]
	s_add_u32 s38, s64, s37
	v_lshl_add_u64 v[26:27], v[26:27], 0, s[6:7]
	s_addc_u32 s39, s65, 0
	s_lshl_b32 s10, s10, 9
	global_load_dwordx4 v[38:41], v[26:27], off
	v_lshl_add_u64 v[28:29], s[38:39], 0, v[106:107]
	s_add_u32 s38, s33, s10
	global_load_dwordx4 v[34:37], v[26:27], off offset:1024
	s_addc_u32 s39, s36, 0
	global_load_dwordx4 v[30:33], v[26:27], off offset:2048
	s_or_b32 s10, s28, 12
	v_lshl_add_u64 v[42:43], v[28:29], 0, s[0:1]
	global_load_dwordx4 v[26:29], v[26:27], off offset:3072
	s_lshl_b32 s37, s10, 16
	v_lshl_add_u64 v[44:45], v[42:43], 0, s[8:9]
	global_load_dwordx2 v[130:131], v[42:43], off
	v_mov_b64_e32 v[42:43], s[38:39]
	s_add_u32 s38, s62, s37
	global_load_dwordx2 v[126:127], v[44:45], off
	s_addc_u32 s39, s63, 0
	s_lshl_b32 s37, s10, 15
	global_load_dword v128, v[42:43], off
	v_lshl_add_u64 v[42:43], s[38:39], 0, v[108:109]
	s_add_u32 s38, s64, s37
	v_lshl_add_u64 v[42:43], v[42:43], 0, s[6:7]
	s_addc_u32 s39, s65, 0
	s_lshl_b32 s10, s10, 9
	global_load_dwordx4 v[54:57], v[42:43], off
	v_lshl_add_u64 v[44:45], s[38:39], 0, v[106:107]
	s_add_u32 s38, s33, s10
	global_load_dwordx4 v[50:53], v[42:43], off offset:1024
	s_addc_u32 s39, s36, 0
	global_load_dwordx4 v[46:49], v[42:43], off offset:2048
	s_or_b32 s10, s28, 16
	v_lshl_add_u64 v[66:67], v[44:45], 0, s[0:1]
	global_load_dwordx4 v[42:45], v[42:43], off offset:3072
	s_lshl_b32 s37, s10, 16
	v_lshl_add_u64 v[68:69], v[66:67], 0, s[8:9]
	global_load_dwordx2 v[134:135], v[66:67], off
	v_mov_b64_e32 v[66:67], s[38:39]
	s_add_u32 s38, s62, s37
	global_load_dwordx2 v[116:117], v[68:69], off
	s_addc_u32 s39, s63, 0
	s_lshl_b32 s37, s10, 15
	global_load_dword v132, v[66:67], off
	v_lshl_add_u64 v[66:67], s[38:39], 0, v[108:109]
	s_add_u32 s38, s64, s37
	v_lshl_add_u64 v[66:67], v[66:67], 0, s[6:7]
	s_addc_u32 s39, s65, 0
	s_lshl_b32 s10, s10, 9
	global_load_dwordx4 v[78:81], v[66:67], off
	v_lshl_add_u64 v[68:69], s[38:39], 0, v[106:107]
	s_add_u32 s38, s33, s10
	global_load_dwordx4 v[74:77], v[66:67], off offset:1024
	s_addc_u32 s39, s36, 0
	global_load_dwordx4 v[70:73], v[66:67], off offset:2048
	s_or_b32 s10, s28, 20
	v_lshl_add_u64 v[82:83], v[68:69], 0, s[0:1]
	global_load_dwordx4 v[66:69], v[66:67], off offset:3072
	s_lshl_b32 s37, s10, 16
	v_lshl_add_u64 v[84:85], v[82:83], 0, s[8:9]
	global_load_dwordx2 v[114:115], v[82:83], off
	v_mov_b64_e32 v[82:83], s[38:39]
	s_add_u32 s38, s62, s37
	global_load_dwordx2 v[110:111], v[84:85], off
	s_addc_u32 s39, s63, 0
	global_load_dword v112, v[82:83], off
	v_lshl_add_u64 v[82:83], s[38:39], 0, v[108:109]
	s_lshl_b32 s37, s10, 15
	v_lshl_add_u64 v[82:83], v[82:83], 0, s[6:7]
	s_add_u32 s38, s64, s37
	global_load_dwordx4 v[94:97], v[82:83], off
	s_addc_u32 s39, s65, 0
	global_load_dwordx4 v[90:93], v[82:83], off offset:1024
	v_lshl_add_u64 v[84:85], s[38:39], 0, v[106:107]
	s_lshl_b32 s10, s10, 9
	global_load_dwordx4 v[86:89], v[82:83], off offset:2048
	v_lshl_add_u64 v[100:101], v[84:85], 0, s[0:1]
	s_add_u32 s38, s33, s10
	global_load_dwordx4 v[82:85], v[82:83], off offset:3072
	v_lshl_add_u64 v[102:103], v[100:101], 0, s[8:9]
	s_addc_u32 s39, s36, 0
	global_load_dwordx2 v[104:105], v[100:101], off
	v_lshlrev_b32_e32 v145, 4, v234
	global_load_dwordx2 v[100:101], v[102:103], off
	v_mov_b64_e32 v[102:103], s[38:39]
	v_add_u32_e32 v1, 0, v145
	s_lshl_b32 s37, s48, 10
	global_load_dword v102, v[102:103], off
	v_add_u32_e32 v103, s0, v1
	s_and_b32 s10, s37, 0xfffff800
	v_add_u32_e32 v129, s10, v103
	s_mov_b32 s38, s1
	s_mov_b32 s39, s1
	s_or_b32 s10, s37, 0x400
	v_mov_b64_e32 v[120:121], s[38:39]
	v_add_u32_e32 v119, s10, v103
	ds_write_b64 v129, v[120:121]
	ds_write_b64 v119, v[120:121]
	s_waitcnt lgkmcnt(0)
	s_barrier
	ds_read_b128 v[120:123], v1 offset:7168
	ds_read_b128 v[146:149], v1 offset:6144
	ds_read_b128 v[150:153], v1 offset:5120
	ds_read_b128 v[154:157], v1 offset:4096
	ds_read_b128 v[158:161], v1 offset:3072
	ds_read_b128 v[162:165], v1 offset:2048
	ds_read_b128 v[166:169], v1 offset:1024
	ds_read_b128 v[170:173], v1
	s_waitcnt vmcnt(35)
	s_add_i32 s10, s37, 0
	v_mul_f32_e32 v118, 0, v113
	v_lshlrev_b32_e32 v174, 16, v124
	v_and_b32_e32 v175, 0xffff0000, v124
	v_lshlrev_b32_e32 v124, 16, v125
	v_and_b32_e32 v125, 0xffff0000, v125
	v_pk_add_f32 v[176:177], v[118:119], v[124:125] op_sel_hi:[0,1]
	v_pk_add_f32 v[174:175], v[118:119], v[174:175] op_sel_hi:[0,1]
	v_lshlrev_b32_e32 v124, 16, v142
	v_and_b32_e32 v125, 0xffff0000, v142
	v_lshlrev_b32_e32 v142, 16, v143
	v_and_b32_e32 v143, 0xffff0000, v143
	s_waitcnt lgkmcnt(0)
	v_mfma_f32_16x16x32_bf16 v[170:173], v[18:21], v[170:173], v[174:177]
	s_lshl_b32 s35, s35, 8
	s_or_b32 s42, s28, 24
	s_or_b32 s11, s35, s11
	v_pk_add_f32 v[176:177], v[118:119], v[142:143] op_sel_hi:[0,1]
	v_pk_add_f32 v[174:175], v[118:119], v[124:125] op_sel_hi:[0,1]
	v_mfma_f32_16x16x32_bf16 v[162:165], v[22:25], v[162:165], v[170:173]
	s_or_b32 s38, s29, 8
	s_or_b32 s39, s29, 9
	s_or_b32 s40, s29, 10
	v_mfma_f32_16x16x32_bf16 v[18:21], v[18:21], v[166:169], v[174:177]
	s_lshl_b32 s35, s29, 17
	s_or_b32 s41, s29, 11
	s_lshl_b32 s28, s42, 16
	v_mfma_f32_16x16x32_bf16 v[18:21], v[22:25], v[158:161], v[18:21]
	v_lshl_add_u64 v[22:23], s[64:65], 0, v[106:107]
	v_lshl_add_u64 v[124:125], v[22:23], 0, s[0:1]
	v_or_b32_e32 v106, s0, v106
	v_mfma_f32_16x16x32_bf16 v[22:25], v[10:13], v[154:157], v[162:165]
	v_add_u32_e32 v155, s10, v145
	s_or_b32 s10, s18, -4
	s_add_u32 s28, s62, s28
	v_mfma_f32_16x16x32_bf16 v[10:13], v[10:13], v[150:153], v[18:21]
	s_addc_u32 s29, s63, 0
	v_mfma_f32_16x16x32_bf16 v[146:149], v[2:5], v[146:149], v[22:25]
	v_mfma_f32_16x16x32_bf16 v[150:153], v[2:5], v[120:123], v[10:13]
	s_nop 0
	s_nop 0
	v_lshl_add_u64 v[2:3], s[28:29], 0, v[108:109]
	v_lshl_add_u64 v[2:3], v[2:3], 0, s[6:7]
	global_load_dwordx4 v[22:25], v[2:3], off
	s_lshl_b32 s28, s42, 15
	s_mov_b32 s29, s1
	global_load_dwordx4 v[18:21], v[2:3], off offset:1024
	v_lshl_add_u64 v[120:121], v[124:125], 0, s[28:29]
	s_lshl_b32 s28, s42, 9
	global_load_dwordx4 v[10:13], v[2:3], off offset:2048
	s_add_u32 s28, s33, s28
	global_load_dwordx4 v[2:5], v[2:3], off offset:3072
	v_lshl_add_u64 v[142:143], v[120:121], 0, s[8:9]
	s_addc_u32 s29, s36, 0
	global_load_dwordx2 v[122:123], v[120:121], off
	global_load_dwordx2 v[120:121], v[142:143], off
	v_mov_b64_e32 v[142:143], s[28:29]
	global_load_dword v118, v[142:143], off
	v_cvt_pk_bf16_f32 v142, v146, v147
	v_cvt_pk_bf16_f32 v143, v148, v149
	ds_write_b64 v129, v[142:143] offset:8192
	v_cvt_pk_bf16_f32 v142, v150, v151
	v_cvt_pk_bf16_f32 v143, v152, v153
	ds_write_b64 v119, v[142:143] offset:8192
	s_waitcnt lgkmcnt(0)
	s_barrier
	ds_read_b128 v[156:159], v1 offset:8192
	ds_read_b128 v[160:163], v1 offset:9216
	ds_read_b128 v[164:167], v1 offset:10240
	ds_read_b128 v[168:171], v1 offset:11264
	ds_read_b128 v[172:175], v1 offset:12288
	ds_read_b128 v[176:179], v1 offset:13312
	ds_read_b128 v[180:183], v1 offset:14336
	ds_read_b128 v[184:187], v1 offset:15360
	ds_read_b128 v[188:191], v155
	s_waitcnt vmcnt(35)
	s_add_i32 s28, s10, s19
	v_lshlrev_b32_e32 v192, 16, v140
	v_and_b32_e32 v193, 0xffff0000, v140
	v_lshlrev_b32_e32 v140, 16, v141
	v_and_b32_e32 v141, 0xffff0000, v141
	v_pk_fma_f32 v[142:143], v[148:149], v[138:139], v[140:141] op_sel_hi:[1,0,1]
	v_pk_fma_f32 v[140:141], v[146:147], v[138:139], v[192:193] op_sel_hi:[1,0,1]
	v_lshlrev_b32_e32 v146, 16, v136
	v_and_b32_e32 v147, 0xffff0000, v136
	v_lshlrev_b32_e32 v136, 16, v137
	v_and_b32_e32 v137, 0xffff0000, v137
	v_pk_fma_f32 v[148:149], v[152:153], v[138:139], v[136:137] op_sel_hi:[1,0,1]
	v_pk_fma_f32 v[146:147], v[150:151], v[138:139], v[146:147] op_sel_hi:[1,0,1]
	s_waitcnt lgkmcnt(8)
	v_mfma_f32_16x16x32_bf16 v[140:143], v[62:65], v[156:159], v[140:143]
	s_lshl_b32 s28, s28, 15
	s_add_i32 s28, s28, 0x20000
	s_mov_b32 s29, s1
	s_waitcnt lgkmcnt(7)
	v_mfma_f32_16x16x32_bf16 v[62:65], v[62:65], v[160:163], v[146:149]
	s_or_b32 s18, s19, s18
	s_waitcnt lgkmcnt(6)
	v_mfma_f32_16x16x32_bf16 v[136:139], v[58:61], v[164:167], v[140:143]
	s_waitcnt lgkmcnt(5)
	v_mfma_f32_16x16x32_bf16 v[58:61], v[58:61], v[168:171], v[62:65]
	s_waitcnt lgkmcnt(4)
	v_mfma_f32_16x16x32_bf16 v[62:65], v[14:17], v[172:175], v[136:139]
	s_waitcnt lgkmcnt(3)
	v_mfma_f32_16x16x32_bf16 v[14:17], v[14:17], v[176:179], v[58:61]
	s_nop 3
	v_or_b32_e32 v58, s3, v234
	v_add_u32_e32 v58, s11, v58
	v_ashrrev_i32_e32 v59, 31, v58
	v_lshl_add_u64 v[148:149], v[58:59], 4, s[64:65]
	s_waitcnt lgkmcnt(2)
	v_mfma_f32_16x16x32_bf16 v[156:159], v[6:9], v[180:183], v[62:65]
	s_waitcnt lgkmcnt(1)
	v_mfma_f32_16x16x32_bf16 v[160:163], v[6:9], v[184:187], v[14:17]
	v_lshl_add_u64 v[6:7], v[148:149], 0, s[28:29]
	s_or_b32 s28, s18, 28
	s_lshl_b32 s18, s28, 16
	s_add_u32 s18, s62, s18
	s_addc_u32 s19, s63, 0
	s_waitcnt lgkmcnt(0)
	global_store_dwordx4 v[6:7], v[188:191], off sc1
	v_lshl_add_u64 v[6:7], s[18:19], 0, v[108:109]
	v_lshl_add_u64 v[6:7], v[6:7], 0, s[6:7]
	global_load_dwordx4 v[62:65], v[6:7], off
	s_lshl_b32 s18, s28, 15
	s_mov_b32 s19, s1
	global_load_dwordx4 v[58:61], v[6:7], off offset:1024
	v_lshl_add_u64 v[136:137], v[124:125], 0, s[18:19]
	s_lshl_b32 s18, s28, 9
	global_load_dwordx4 v[14:17], v[6:7], off offset:2048
	s_add_u32 s18, s33, s18
	global_load_dwordx4 v[6:9], v[6:7], off offset:3072
	s_addc_u32 s19, s36, 0
	global_load_dwordx2 v[150:151], v[136:137], off
	v_lshl_add_u64 v[138:139], v[136:137], 0, s[8:9]
	global_load_dwordx2 v[140:141], v[138:139], off
	v_mov_b64_e32 v[136:137], s[18:19]
	global_load_dword v138, v[136:137], off
	v_cvt_pk_bf16_f32 v136, v156, v157
	v_cvt_pk_bf16_f32 v137, v158, v159
	ds_write_b64 v129, v[136:137] offset:16384
	v_cvt_pk_bf16_f32 v136, v160, v161
	v_cvt_pk_bf16_f32 v137, v162, v163
	ds_write_b64 v119, v[136:137] offset:16384
	s_waitcnt lgkmcnt(0)
	s_barrier
	ds_read_b128 v[164:167], v1 offset:16384
	ds_read_b128 v[168:171], v1 offset:17408
	ds_read_b128 v[172:175], v1 offset:18432
	ds_read_b128 v[176:179], v1 offset:19456
	ds_read_b128 v[180:183], v1 offset:20480
	ds_read_b128 v[184:187], v1 offset:21504
	ds_read_b128 v[188:191], v1 offset:22528
	ds_read_b128 v[192:195], v1 offset:23552
	ds_read_b128 v[196:199], v155 offset:8192
	s_waitcnt vmcnt(35)
	s_lshl_b32 s18, s10, 15
	v_lshlrev_b32_e32 v136, 16, v130
	v_and_b32_e32 v137, 0xffff0000, v130
	v_lshlrev_b32_e32 v130, 16, v131
	v_and_b32_e32 v131, 0xffff0000, v131
	v_pk_fma_f32 v[158:159], v[158:159], v[128:129], v[130:131] op_sel_hi:[1,0,1]
	v_lshlrev_b32_e32 v130, 16, v126
	v_and_b32_e32 v131, 0xffff0000, v126
	v_lshlrev_b32_e32 v126, 16, v127
	v_and_b32_e32 v127, 0xffff0000, v127
	v_pk_fma_f32 v[156:157], v[156:157], v[128:129], v[136:137] op_sel_hi:[1,0,1]
	v_pk_fma_f32 v[162:163], v[162:163], v[128:129], v[126:127] op_sel_hi:[1,0,1]
	v_pk_fma_f32 v[160:161], v[160:161], v[128:129], v[130:131] op_sel_hi:[1,0,1]
	s_waitcnt lgkmcnt(8)
	v_mfma_f32_16x16x32_bf16 v[156:159], v[38:41], v[164:167], v[156:159]
	s_add_i32 s18, s18, s35
	s_lshl_b32 s19, s38, 2
	s_add_i32 s28, s18, 0x40000
	s_waitcnt lgkmcnt(7)
	v_mfma_f32_16x16x32_bf16 v[38:41], v[38:41], v[168:171], v[160:163]
	s_or_b32 s19, s19, s5
	s_waitcnt lgkmcnt(6)
	v_mfma_f32_16x16x32_bf16 v[156:159], v[34:37], v[172:175], v[156:159]
	s_waitcnt lgkmcnt(5)
	v_mfma_f32_16x16x32_bf16 v[34:37], v[34:37], v[176:179], v[38:41]
	s_waitcnt lgkmcnt(4)
	v_mfma_f32_16x16x32_bf16 v[38:41], v[30:33], v[180:183], v[156:159]
	s_waitcnt lgkmcnt(3)
	v_mfma_f32_16x16x32_bf16 v[30:33], v[30:33], v[184:187], v[34:37]
	s_waitcnt lgkmcnt(2)
	v_mfma_f32_16x16x32_bf16 v[156:159], v[26:29], v[188:191], v[38:41]
	s_waitcnt lgkmcnt(1)
	v_mfma_f32_16x16x32_bf16 v[160:163], v[26:29], v[192:195], v[30:33]
	v_lshl_add_u64 v[26:27], v[148:149], 0, s[28:29]
	s_lshl_b32 s28, s19, 16
	s_add_u32 s28, s62, s28
	s_addc_u32 s29, s63, 0
	s_waitcnt lgkmcnt(0)
	global_store_dwordx4 v[26:27], v[196:199], off sc1
	v_lshl_add_u64 v[26:27], s[28:29], 0, v[108:109]
	v_lshl_add_u64 v[26:27], v[26:27], 0, s[6:7]
	global_load_dwordx4 v[38:41], v[26:27], off
	global_load_dwordx4 v[34:37], v[26:27], off offset:1024
	s_lshl_b32 s28, s19, 15
	s_mov_b32 s29, s1
	s_lshl_b32 s19, s19, 9
	global_load_dwordx4 v[30:33], v[26:27], off offset:2048
	v_lshl_add_u64 v[126:127], v[124:125], 0, s[28:29]
	s_add_u32 s28, s33, s19
	global_load_dwordx4 v[26:29], v[26:27], off offset:3072
	v_lshl_add_u64 v[136:137], v[126:127], 0, s[8:9]
	s_addc_u32 s29, s36, 0
	global_load_dwordx2 v[130:131], v[126:127], off
	global_load_dwordx2 v[126:127], v[136:137], off
	v_mov_b64_e32 v[136:137], s[28:29]
	global_load_dword v128, v[136:137], off
	v_cvt_pk_bf16_f32 v136, v156, v157
	v_cvt_pk_bf16_f32 v137, v158, v159
	ds_write_b64 v129, v[136:137]
	v_cvt_pk_bf16_f32 v136, v160, v161
	v_cvt_pk_bf16_f32 v137, v162, v163
	ds_write_b64 v119, v[136:137]
	s_waitcnt lgkmcnt(0)
	s_barrier
	ds_read_b128 v[164:167], v1
	ds_read_b128 v[168:171], v1 offset:1024
	ds_read_b128 v[172:175], v1 offset:2048
	ds_read_b128 v[176:179], v1 offset:3072
	ds_read_b128 v[180:183], v1 offset:4096
	ds_read_b128 v[184:187], v1 offset:5120
	ds_read_b128 v[188:191], v1 offset:6144
	ds_read_b128 v[192:195], v1 offset:7168
	ds_read_b128 v[196:199], v155 offset:16384
	s_waitcnt vmcnt(35)
	s_lshl_b32 s19, s39, 2
	v_lshlrev_b32_e32 v142, 16, v134
	v_and_b32_e32 v143, 0xffff0000, v134
	v_lshlrev_b32_e32 v134, 16, v135
	v_and_b32_e32 v135, 0xffff0000, v135
	v_pk_fma_f32 v[136:137], v[158:159], v[132:133], v[134:135] op_sel_hi:[1,0,1]
	v_pk_fma_f32 v[134:135], v[156:157], v[132:133], v[142:143] op_sel_hi:[1,0,1]
	v_lshlrev_b32_e32 v142, 16, v116
	v_and_b32_e32 v143, 0xffff0000, v116
	v_lshlrev_b32_e32 v116, 16, v117
	v_and_b32_e32 v117, 0xffff0000, v117
	v_pk_fma_f32 v[158:159], v[162:163], v[132:133], v[116:117] op_sel_hi:[1,0,1]
	v_pk_fma_f32 v[156:157], v[160:161], v[132:133], v[142:143] op_sel_hi:[1,0,1]
	s_waitcnt lgkmcnt(8)
	v_mfma_f32_16x16x32_bf16 v[134:137], v[54:57], v[164:167], v[134:137]
	s_add_i32 s28, s18, 0x60000
	s_mov_b32 s29, s1
	s_or_b32 s19, s19, s5
	s_waitcnt lgkmcnt(7)
	v_mfma_f32_16x16x32_bf16 v[54:57], v[54:57], v[168:171], v[156:159]
	s_waitcnt lgkmcnt(6)
	v_mfma_f32_16x16x32_bf16 v[132:135], v[50:53], v[172:175], v[134:137]
	s_waitcnt lgkmcnt(5)
	v_mfma_f32_16x16x32_bf16 v[50:53], v[50:53], v[176:179], v[54:57]
	s_waitcnt lgkmcnt(4)
	v_mfma_f32_16x16x32_bf16 v[54:57], v[46:49], v[180:183], v[132:135]
	s_waitcnt lgkmcnt(3)
	v_mfma_f32_16x16x32_bf16 v[46:49], v[46:49], v[184:187], v[50:53]
	s_waitcnt lgkmcnt(2)
	v_mfma_f32_16x16x32_bf16 v[156:159], v[42:45], v[188:191], v[54:57]
	s_waitcnt lgkmcnt(1)
	v_mfma_f32_16x16x32_bf16 v[160:163], v[42:45], v[192:195], v[46:49]
	v_lshl_add_u64 v[42:43], v[148:149], 0, s[28:29]
	s_lshl_b32 s28, s19, 16
	s_add_u32 s28, s62, s28
	s_addc_u32 s29, s63, 0
	s_waitcnt lgkmcnt(0)
	global_store_dwordx4 v[42:43], v[196:199], off sc1
	v_lshl_add_u64 v[42:43], s[28:29], 0, v[108:109]
	v_lshl_add_u64 v[42:43], v[42:43], 0, s[6:7]
	global_load_dwordx4 v[54:57], v[42:43], off
	global_load_dwordx4 v[50:53], v[42:43], off offset:1024
	s_lshl_b32 s28, s19, 15
	s_mov_b32 s29, s1
	s_lshl_b32 s19, s19, 9
	global_load_dwordx4 v[46:49], v[42:43], off offset:2048
	v_lshl_add_u64 v[116:117], v[124:125], 0, s[28:29]
	s_add_u32 s28, s33, s19
	global_load_dwordx4 v[42:45], v[42:43], off offset:3072
	v_lshl_add_u64 v[132:133], v[116:117], 0, s[8:9]
	s_addc_u32 s29, s36, 0
	global_load_dwordx2 v[136:137], v[116:117], off
	global_load_dwordx2 v[132:133], v[132:133], off
	v_mov_b64_e32 v[116:117], s[28:29]
	global_load_dword v134, v[116:117], off
	v_cvt_pk_bf16_f32 v116, v156, v157
	v_cvt_pk_bf16_f32 v117, v158, v159
	ds_write_b64 v129, v[116:117] offset:8192
	v_cvt_pk_bf16_f32 v116, v160, v161
	v_cvt_pk_bf16_f32 v117, v162, v163
	ds_write_b64 v119, v[116:117] offset:8192
	s_waitcnt lgkmcnt(0)
	s_barrier
	ds_read_b128 v[164:167], v1 offset:8192
	ds_read_b128 v[168:171], v1 offset:9216
	ds_read_b128 v[172:175], v1 offset:10240
	ds_read_b128 v[176:179], v1 offset:11264
	ds_read_b128 v[180:183], v1 offset:12288
	ds_read_b128 v[184:187], v1 offset:13312
	ds_read_b128 v[188:191], v1 offset:14336
	ds_read_b128 v[192:195], v1 offset:15360
	ds_read_b128 v[196:199], v155
	s_waitcnt vmcnt(35)
	s_lshl_b32 s19, s40, 2
	v_lshlrev_b32_e32 v142, 16, v114
	v_and_b32_e32 v143, 0xffff0000, v114
	v_lshlrev_b32_e32 v114, 16, v115
	v_and_b32_e32 v115, 0xffff0000, v115
	v_pk_fma_f32 v[116:117], v[158:159], v[112:113], v[114:115] op_sel_hi:[1,0,1]
	v_pk_fma_f32 v[114:115], v[156:157], v[112:113], v[142:143] op_sel_hi:[1,0,1]
	v_lshlrev_b32_e32 v142, 16, v110
	v_and_b32_e32 v143, 0xffff0000, v110
	v_lshlrev_b32_e32 v110, 16, v111
	v_and_b32_e32 v111, 0xffff0000, v111
	v_pk_fma_f32 v[158:159], v[162:163], v[112:113], v[110:111] op_sel_hi:[1,0,1]
	v_pk_fma_f32 v[156:157], v[160:161], v[112:113], v[142:143] op_sel_hi:[1,0,1]
	s_waitcnt lgkmcnt(8)
	v_mfma_f32_16x16x32_bf16 v[114:117], v[78:81], v[164:167], v[114:117]
	s_add_i32 s28, s18, 0x80000
	s_mov_b32 s29, s1
	s_or_b32 s19, s19, s5
	s_waitcnt lgkmcnt(7)
	v_mfma_f32_16x16x32_bf16 v[78:81], v[78:81], v[168:171], v[156:159]
	s_waitcnt lgkmcnt(6)
	v_mfma_f32_16x16x32_bf16 v[110:113], v[74:77], v[172:175], v[114:117]
	s_waitcnt lgkmcnt(5)
	v_mfma_f32_16x16x32_bf16 v[74:77], v[74:77], v[176:179], v[78:81]
	s_waitcnt lgkmcnt(4)
	v_mfma_f32_16x16x32_bf16 v[78:81], v[70:73], v[180:183], v[110:113]
	s_waitcnt lgkmcnt(3)
	v_mfma_f32_16x16x32_bf16 v[70:73], v[70:73], v[184:187], v[74:77]
	s_waitcnt lgkmcnt(2)
	v_mfma_f32_16x16x32_bf16 v[110:113], v[66:69], v[188:191], v[78:81]
	s_waitcnt lgkmcnt(1)
	v_mfma_f32_16x16x32_bf16 v[114:117], v[66:69], v[192:195], v[70:73]
	v_lshl_add_u64 v[66:67], v[148:149], 0, s[28:29]
	s_lshl_b32 s28, s19, 16
	s_add_u32 s28, s62, s28
	s_addc_u32 s29, s63, 0
	s_waitcnt lgkmcnt(0)
	global_store_dwordx4 v[66:67], v[196:199], off sc1
	v_lshl_add_u64 v[66:67], s[28:29], 0, v[108:109]
	v_lshl_add_u64 v[66:67], v[66:67], 0, s[6:7]
	global_load_dwordx4 v[78:81], v[66:67], off
	global_load_dwordx4 v[74:77], v[66:67], off offset:1024
	s_lshl_b32 s28, s19, 15
	s_mov_b32 s29, s1
	s_lshl_b32 s19, s19, 9
	global_load_dwordx4 v[70:73], v[66:67], off offset:2048
	v_lshl_add_u64 v[142:143], v[124:125], 0, s[28:29]
	s_add_u32 s28, s33, s19
	global_load_dwordx4 v[66:69], v[66:67], off offset:3072
	v_lshl_add_u64 v[152:153], v[142:143], 0, s[8:9]
	s_addc_u32 s29, s36, 0
	global_load_dwordx2 v[146:147], v[142:143], off
	global_load_dwordx2 v[142:143], v[152:153], off
	v_mov_b64_e32 v[152:153], s[28:29]
	global_load_dword v144, v[152:153], off
	v_cvt_pk_bf16_f32 v152, v110, v111
	v_cvt_pk_bf16_f32 v153, v112, v113
	ds_write_b64 v129, v[152:153] offset:16384
	v_cvt_pk_bf16_f32 v152, v114, v115
	v_cvt_pk_bf16_f32 v153, v116, v117
	ds_write_b64 v119, v[152:153] offset:16384
	s_waitcnt lgkmcnt(0)
	s_barrier
;     const int b = job >> 4, h = (job >> 2) & 3, sl = job & 3;
;     f32x4 acc[2]; acc[0] = (f32x4){0.f, 0.f, 0.f, 0.f}; acc[1] = acc[0];
;     DnPre p0, p1, p2, p3, p4, p5;
;     DN_ISSUE(p0, 0); DN_ISSUE(p1, 1); DN_ISSUE(p2, 2); DN_ISSUE(p3, 3); DN_ISSUE(p4, 4); DN_ISSUE(p5, 5);
;     for (int n0 = 0; n0 < 126; n0 += 6) {
;         DN_STEP(p0, n0, 0, true, MODE); DN_STEP(p1, n0 + 1, 1, true, MODE); DN_STEP(p2, n0 + 2, 2, true, MODE); DN_STEP(p3, n0 + 3, 0, true, MODE); DN_STEP(p4, n0 + 4, 1, true, MODE); DN_STEP(p5, n0 + 5, 2, true, MODE);
	ds_read_b128 v[156:159], v1 offset:16384
	ds_read_b128 v[160:163], v1 offset:17408
	ds_read_b128 v[164:167], v1 offset:18432
	ds_read_b128 v[168:171], v1 offset:19456
	ds_read_b128 v[172:175], v1 offset:20480
	ds_read_b128 v[176:179], v1 offset:21504
	ds_read_b128 v[180:183], v1 offset:22528
	ds_read_b128 v[184:187], v1 offset:23552
	ds_read_b128 v[188:191], v155 offset:8192
	s_waitcnt vmcnt(35)
	s_add_i32 s18, s18, 0xa0000
	v_lshlrev_b32_e32 v152, 16, v104
	v_and_b32_e32 v153, 0xffff0000, v104
	v_lshlrev_b32_e32 v104, 16, v105
	v_and_b32_e32 v105, 0xffff0000, v105
	v_pk_fma_f32 v[110:111], v[110:111], v[102:103], v[152:153] op_sel_hi:[1,0,1]
	v_lshlrev_b32_e32 v152, 16, v100
	v_and_b32_e32 v153, 0xffff0000, v100
	v_lshlrev_b32_e32 v100, 16, v101
	v_and_b32_e32 v101, 0xffff0000, v101
	v_pk_fma_f32 v[112:113], v[112:113], v[102:103], v[104:105] op_sel_hi:[1,0,1]
	v_pk_fma_f32 v[104:105], v[116:117], v[102:103], v[100:101] op_sel_hi:[1,0,1]
	v_pk_fma_f32 v[102:103], v[114:115], v[102:103], v[152:153] op_sel_hi:[1,0,1]
	s_waitcnt lgkmcnt(8)
	v_mfma_f32_16x16x32_bf16 v[110:113], v[94:97], v[156:159], v[110:113]
	s_mov_b32 s19, s1
	s_waitcnt lgkmcnt(7)
	v_mfma_f32_16x16x32_bf16 v[94:97], v[94:97], v[160:163], v[102:105]
	s_waitcnt lgkmcnt(6)
	v_mfma_f32_16x16x32_bf16 v[100:103], v[90:93], v[164:167], v[110:113]
	s_waitcnt lgkmcnt(5)
	v_mfma_f32_16x16x32_bf16 v[90:93], v[90:93], v[168:171], v[94:97]
	s_nop 0
	v_lshlrev_b64 v[110:111], 3, v[98:99]
	s_waitcnt lgkmcnt(4)
	v_mfma_f32_16x16x32_bf16 v[94:97], v[86:89], v[172:175], v[100:103]
	v_lshlrev_b64 v[174:175], 1, v[110:111]
	s_waitcnt lgkmcnt(3)
	v_mfma_f32_16x16x32_bf16 v[86:89], v[86:89], v[176:179], v[90:93]
	s_waitcnt lgkmcnt(2)
	v_mfma_f32_16x16x32_bf16 v[102:105], v[82:85], v[180:183], v[94:97]
	s_waitcnt lgkmcnt(1)
	v_mfma_f32_16x16x32_bf16 v[98:101], v[82:85], v[184:187], v[86:89]
	v_lshl_add_u64 v[82:83], v[148:149], 0, s[18:19]
	s_lshl_b32 s18, s41, 2
	s_or_b32 s28, s18, s5
	s_lshl_b32 s18, s28, 16
	s_add_u32 s18, s62, s18
	s_addc_u32 s19, s63, 0
	s_waitcnt lgkmcnt(0)
	global_store_dwordx4 v[82:83], v[188:191], off sc1
	v_lshl_add_u64 v[82:83], s[18:19], 0, v[108:109]
	s_lshl_b32 s18, s28, 15
	s_mov_b32 s19, s1
	v_lshl_add_u64 v[82:83], v[82:83], 0, s[6:7]
	v_lshl_add_u64 v[108:109], v[124:125], 0, s[18:19]
	s_lshl_b32 s18, s28, 9
	global_load_dwordx4 v[94:97], v[82:83], off
	s_add_u32 s18, s33, s18
	global_load_dwordx4 v[90:93], v[82:83], off offset:1024
	s_addc_u32 s19, s36, 0
	global_load_dwordx4 v[86:89], v[82:83], off offset:2048
	s_add_i32 s11, s11, s3
	s_lshl_b32 s3, s2, 7
	global_load_dwordx4 v[82:85], v[82:83], off offset:3072
	s_and_b32 s3, s3, 0x200
	global_load_dwordx2 v[156:157], v[108:109], off
	v_or_b32_e32 v148, s11, v234
	s_add_i32 s10, s10, s3
	v_lshl_add_u64 v[112:113], v[108:109], 0, s[8:9]
	global_load_dwordx2 v[152:153], v[112:113], off
	v_mov_b64_e32 v[108:109], s[18:19]
	v_ashrrev_i32_e32 v149, 31, v148
	s_lshl_b32 s45, s10, 15
	global_load_dword v154, v[108:109], off
	v_lshlrev_b64 v[108:109], 4, v[148:149]
	s_add_i32 s10, s45, 0xe0000
	s_mov_b32 s11, s1
	v_lshl_add_u64 v[112:113], v[108:109], 0, s[10:11]
	s_mov_b64 s[28:29], 0xc00000
	s_add_i32 s10, s45, 0x160000
	v_lshl_add_u64 v[158:159], v[112:113], 0, s[28:29]
	v_lshl_add_u64 v[112:113], v[108:109], 0, s[10:11]
	s_add_i32 s10, s45, 0x140000
	v_lshl_add_u64 v[160:161], v[112:113], 0, s[28:29]
	v_lshl_add_u64 v[112:113], v[108:109], 0, s[10:11]
	s_add_i32 s10, s45, 0x120000
	v_lshl_add_u64 v[162:163], v[112:113], 0, s[28:29]
	v_lshl_add_u64 v[112:113], v[108:109], 0, s[10:11]
	s_add_i32 s10, s45, 0x100000
	s_or_b32 s3, s3, s5
	v_lshl_add_u64 v[164:165], v[112:113], 0, s[28:29]
	v_lshl_add_u64 v[112:113], v[108:109], 0, s[10:11]
	s_or_b32 s10, s3, 52
	s_lshl_b32 s11, s10, 16
	s_add_u32 s35, s11, 0xa004000
	s_addc_u32 s42, 0, 0
	s_lshl_b32 s0, s10, 15
	v_lshl_add_u64 v[166:167], v[112:113], 0, s[28:29]
	v_lshl_add_u64 v[112:113], v[106:107], 0, s[0:1]
	s_lshl_b32 s0, s10, 9
	s_add_u32 s10, s33, s0
	s_addc_u32 s11, s36, 0
	s_or_b32 s3, s3, 48
	s_lshl_b32 s0, s3, 16
	s_add_u32 s43, s0, 0xa004000
	s_addc_u32 s44, 0, 0
	s_lshl_b32 s0, s3, 15
	v_lshl_add_u64 v[106:107], v[106:107], 0, s[0:1]
	s_lshl_b32 s0, s3, 9
	s_add_u32 s18, s33, s0
	s_addc_u32 s19, s36, 0
	s_add_i32 s0, s45, 0xc0000
	v_lshl_add_u64 v[170:171], v[106:107], 0, s[28:29]
	v_lshl_add_u64 v[106:107], v[108:109], 0, s[0:1]
	v_lshl_add_u64 v[168:169], v[112:113], 0, s[28:29]
	v_lshl_add_u64 v[172:173], v[106:107], 0, s[28:29]
	s_mov_b64 s[28:29], 0xc0000
	s_mov_b32 s45, 0
.LBB0_675:
	s_nop 0
	v_cvt_pk_bf16_f32 v106, v102, v103
	v_cvt_pk_bf16_f32 v107, v104, v105
	s_nop 1
	v_cvt_pk_bf16_f32 v108, v98, v99
	v_cvt_pk_bf16_f32 v109, v100, v101
	ds_write_b64 v129, v[106:107]
	ds_write_b64 v119, v[108:109]
	s_waitcnt lgkmcnt(0)
	s_barrier
	ds_read_b128 v[106:109], v1
	ds_read_b128 v[110:113], v1 offset:1024
	ds_read_b128 v[114:117], v1 offset:2048
	ds_read_b128 v[176:179], v1 offset:3072
	ds_read_b128 v[180:183], v1 offset:4096
	ds_read_b128 v[184:187], v1 offset:5120
	ds_read_b128 v[188:191], v1 offset:6144
	ds_read_b128 v[192:195], v1 offset:7168
	ds_read_b128 v[196:199], v155 offset:16384
	s_waitcnt vmcnt(35)
	s_add_i32 s45, s45, 6
	v_lshlrev_b32_e32 v200, 16, v122
	v_and_b32_e32 v201, 0xffff0000, v122
	v_lshlrev_b32_e32 v122, 16, v123
	v_and_b32_e32 v123, 0xffff0000, v123
	v_lshlrev_b32_e32 v202, 16, v120
	v_and_b32_e32 v203, 0xffff0000, v120
	v_lshlrev_b32_e32 v120, 16, v121
	v_and_b32_e32 v121, 0xffff0000, v121
	v_pk_fma_f32 v[104:105], v[104:105], v[118:119], v[122:123] op_sel_hi:[1,0,1]
	v_pk_fma_f32 v[102:103], v[102:103], v[118:119], v[200:201] op_sel_hi:[1,0,1]
	v_pk_fma_f32 v[100:101], v[100:101], v[118:119], v[120:121] op_sel_hi:[1,0,1]
	v_pk_fma_f32 v[98:99], v[98:99], v[118:119], v[202:203] op_sel_hi:[1,0,1]
	s_waitcnt lgkmcnt(8)
	v_mfma_f32_16x16x32_bf16 v[102:105], v[22:25], v[106:109], v[102:105]
	s_add_u32 s46, s60, s43
	s_addc_u32 s47, s61, s44
	v_lshl_add_u64 v[106:107], s[46:47], 0, v[174:175]
	s_waitcnt lgkmcnt(7)
	v_mfma_f32_16x16x32_bf16 v[22:25], v[22:25], v[110:113], v[98:101]
	s_add_u32 s46, s60, s35
	s_addc_u32 s47, s61, s42
	s_min_u32 s0, s45, 0x77
	s_waitcnt lgkmcnt(6)
	v_mfma_f32_16x16x32_bf16 v[98:101], v[18:21], v[114:117], v[102:105]
	s_add_i32 s0, s0, s38
	s_lshl_b32 s0, s0, 2
	s_or_b32 s3, s0, s5
	s_waitcnt lgkmcnt(5)
	v_mfma_f32_16x16x32_bf16 v[18:21], v[18:21], v[176:179], v[22:25]
	v_mov_b64_e32 v[102:103], s[18:19]
	s_lshl_b32 s0, s3, 16
	s_waitcnt lgkmcnt(4)
	v_mfma_f32_16x16x32_bf16 v[22:25], v[10:13], v[180:183], v[98:101]
	s_waitcnt lgkmcnt(3)
	v_mfma_f32_16x16x32_bf16 v[10:13], v[10:13], v[184:187], v[18:21]
	s_nop 0
	v_lshl_add_u64 v[98:99], s[60:61], 0, v[172:173]
	v_lshl_add_u64 v[100:101], s[60:61], 0, v[170:171]
	v_lshl_add_u64 v[104:105], v[100:101], 0, s[8:9]
	s_waitcnt lgkmcnt(2)
	v_mfma_f32_16x16x32_bf16 v[176:179], v[2:5], v[188:191], v[22:25]
	v_lshl_add_u64 v[170:171], v[170:171], 0, s[28:29]
	v_lshl_add_u64 v[172:173], v[172:173], 0, s[28:29]
	s_waitcnt lgkmcnt(1)
	v_mfma_f32_16x16x32_bf16 v[180:183], v[2:5], v[192:195], v[10:13]
	s_waitcnt lgkmcnt(0)
	global_store_dwordx4 v[98:99], v[196:199], off sc1
	global_load_dwordx4 v[22:25], v[106:107], off
	global_load_dwordx4 v[18:21], v[106:107], off offset:1024
	global_load_dwordx4 v[10:13], v[106:107], off offset:2048
	global_load_dwordx4 v[2:5], v[106:107], off offset:3072
	global_load_dwordx2 v[122:123], v[100:101], off
	s_nop 1
	v_cvt_pk_bf16_f32 v98, v176, v177
	v_cvt_pk_bf16_f32 v99, v178, v179
	global_load_dwordx2 v[120:121], v[104:105], off
	s_nop 1
	v_cvt_pk_bf16_f32 v108, v180, v181
	v_cvt_pk_bf16_f32 v109, v182, v183
	global_load_dword v118, v[102:103], off
	ds_write_b64 v129, v[98:99] offset:8192
	ds_write_b64 v119, v[108:109] offset:8192
	s_waitcnt lgkmcnt(0)
	s_barrier
	ds_read_b128 v[184:187], v1 offset:8192
	ds_read_b128 v[188:191], v1 offset:9216
	ds_read_b128 v[192:195], v1 offset:10240
	ds_read_b128 v[196:199], v1 offset:11264
	ds_read_b128 v[114:117], v1 offset:12288
	ds_read_b128 v[110:113], v1 offset:13312
	ds_read_b128 v[106:109], v1 offset:14336
	ds_read_b128 v[102:105], v1 offset:15360
	ds_read_b128 v[98:101], v155
	s_waitcnt vmcnt(35)
	s_nop 0
	v_lshlrev_b32_e32 v200, 16, v150
	v_and_b32_e32 v201, 0xffff0000, v150
	v_lshlrev_b32_e32 v150, 16, v151
	v_and_b32_e32 v151, 0xffff0000, v151
	v_lshlrev_b32_e32 v202, 16, v140
	v_and_b32_e32 v203, 0xffff0000, v140
	v_lshlrev_b32_e32 v140, 16, v141
	v_and_b32_e32 v141, 0xffff0000, v141
	v_pk_fma_f32 v[178:179], v[178:179], v[138:139], v[150:151] op_sel_hi:[1,0,1]
	v_pk_fma_f32 v[176:177], v[176:177], v[138:139], v[200:201] op_sel_hi:[1,0,1]
	v_pk_fma_f32 v[140:141], v[182:183], v[138:139], v[140:141] op_sel_hi:[1,0,1]
	v_pk_fma_f32 v[138:139], v[180:181], v[138:139], v[202:203] op_sel_hi:[1,0,1]
	s_waitcnt lgkmcnt(8)
	v_mfma_f32_16x16x32_bf16 v[176:179], v[62:65], v[184:187], v[176:179]
	s_waitcnt lgkmcnt(7)
	v_mfma_f32_16x16x32_bf16 v[180:183], v[62:65], v[188:191], v[138:141]
	s_waitcnt lgkmcnt(6)
	v_mfma_f32_16x16x32_bf16 v[62:65], v[58:61], v[192:195], v[176:179]
	s_nop 0
	v_lshl_add_u64 v[140:141], s[60:61], 0, v[158:159]
	v_lshl_add_u64 v[138:139], s[60:61], 0, v[168:169]
	v_lshl_add_u64 v[158:159], v[158:159], 0, s[28:29]
	s_waitcnt lgkmcnt(5)
	v_mfma_f32_16x16x32_bf16 v[58:61], v[58:61], v[196:199], v[180:183]
	v_mov_b64_e32 v[176:177], s[10:11]
	v_lshl_add_u64 v[178:179], s[60:61], 0, v[166:167]
	v_lshl_add_u64 v[166:167], v[166:167], 0, s[28:29]
	s_waitcnt lgkmcnt(4)
	v_mfma_f32_16x16x32_bf16 v[62:65], v[14:17], v[114:117], v[62:65]
	v_lshl_add_u64 v[180:181], s[60:61], 0, v[164:165]
	v_lshl_add_u64 v[182:183], s[60:61], 0, v[162:163]
	v_lshl_add_u64 v[114:115], s[60:61], 0, v[160:161]
	s_waitcnt lgkmcnt(3)
	v_mfma_f32_16x16x32_bf16 v[14:17], v[14:17], v[110:113], v[58:61]
	v_lshl_add_u64 v[112:113], s[46:47], 0, v[174:175]
	v_lshl_add_u64 v[110:111], v[138:139], 0, s[8:9]
	s_add_u32 s46, s62, s0
	s_waitcnt lgkmcnt(2)
	v_mfma_f32_16x16x32_bf16 v[106:109], v[6:9], v[106:109], v[62:65]
	s_addc_u32 s47, s63, 0
	s_lshl_b32 s0, s3, 15
	s_lshl_b32 s3, s3, 9
	s_waitcnt lgkmcnt(1)
	v_mfma_f32_16x16x32_bf16 v[102:105], v[6:9], v[102:105], v[14:17]
	s_waitcnt lgkmcnt(0)
	global_store_dwordx4 v[140:141], v[98:101], off sc1
	global_load_dwordx4 v[62:65], v[112:113], off
	global_load_dwordx4 v[58:61], v[112:113], off offset:1024
	global_load_dwordx4 v[14:17], v[112:113], off offset:2048
	global_load_dwordx4 v[6:9], v[112:113], off offset:3072
	global_load_dwordx2 v[150:151], v[138:139], off
	s_nop 1
	v_cvt_pk_bf16_f32 v98, v106, v107
	v_cvt_pk_bf16_f32 v99, v108, v109
	global_load_dwordx2 v[140:141], v[110:111], off
	s_nop 1
	v_cvt_pk_bf16_f32 v100, v102, v103
	v_cvt_pk_bf16_f32 v101, v104, v105
	global_load_dword v138, v[176:177], off
	ds_write_b64 v129, v[98:99] offset:16384
	ds_write_b64 v119, v[100:101] offset:16384
	s_waitcnt lgkmcnt(0)
	s_barrier
	ds_read_b128 v[98:101], v1 offset:16384
	ds_read_b128 v[110:113], v1 offset:17408
	ds_read_b128 v[184:187], v1 offset:18432
	ds_read_b128 v[188:191], v1 offset:19456
	ds_read_b128 v[192:195], v1 offset:20480
	ds_read_b128 v[196:199], v1 offset:21504
	ds_read_b128 v[200:203], v1 offset:22528
	ds_read_b128 v[204:207], v1 offset:23552
	ds_read_b128 v[208:211], v155 offset:8192
	s_waitcnt vmcnt(35)
	v_lshl_add_u64 v[160:161], v[160:161], 0, s[28:29]
	v_lshlrev_b32_e32 v116, 16, v130
	v_and_b32_e32 v117, 0xffff0000, v130
	v_lshlrev_b32_e32 v130, 16, v131
	v_and_b32_e32 v131, 0xffff0000, v131
	v_lshlrev_b32_e32 v176, 16, v126
	v_and_b32_e32 v177, 0xffff0000, v126
	v_lshlrev_b32_e32 v126, 16, v127
	v_and_b32_e32 v127, 0xffff0000, v127
	v_pk_fma_f32 v[108:109], v[108:109], v[128:129], v[130:131] op_sel_hi:[1,0,1]
	v_pk_fma_f32 v[106:107], v[106:107], v[128:129], v[116:117] op_sel_hi:[1,0,1]
	v_pk_fma_f32 v[104:105], v[104:105], v[128:129], v[126:127] op_sel_hi:[1,0,1]
	v_pk_fma_f32 v[102:103], v[102:103], v[128:129], v[176:177] op_sel_hi:[1,0,1]
	s_waitcnt lgkmcnt(8)
	v_mfma_f32_16x16x32_bf16 v[98:101], v[38:41], v[98:101], v[106:109]
	v_lshl_add_u64 v[162:163], v[162:163], 0, s[28:29]
	v_lshl_add_u64 v[164:165], v[164:165], 0, s[28:29]
	v_lshl_add_u64 v[168:169], v[168:169], 0, s[28:29]
	s_waitcnt lgkmcnt(7)
	v_mfma_f32_16x16x32_bf16 v[38:41], v[38:41], v[110:113], v[102:105]
	v_lshl_add_u64 v[106:107], v[124:125], 0, s[0:1]
	v_lshl_add_u64 v[110:111], v[106:107], 0, s[8:9]
	s_waitcnt lgkmcnt(6)
	v_mfma_f32_16x16x32_bf16 v[98:101], v[34:37], v[184:187], v[98:101]
	s_waitcnt lgkmcnt(5)
	v_mfma_f32_16x16x32_bf16 v[34:37], v[34:37], v[188:191], v[38:41]
	s_waitcnt lgkmcnt(4)
	v_mfma_f32_16x16x32_bf16 v[38:41], v[30:33], v[192:195], v[98:101]
	s_waitcnt lgkmcnt(3)
	v_mfma_f32_16x16x32_bf16 v[30:33], v[30:33], v[196:199], v[34:37]
	s_nop 1
	v_lshl_add_u64 v[98:99], s[46:47], 0, v[174:175]
	v_lshl_add_u64 v[108:109], v[98:99], 0, s[6:7]
	s_add_u32 s46, s33, s3
	s_waitcnt lgkmcnt(2)
	v_mfma_f32_16x16x32_bf16 v[98:101], v[26:29], v[200:203], v[38:41]
	s_addc_u32 s47, s36, 0
	v_mov_b64_e32 v[112:113], s[46:47]
	s_min_u32 s0, s45, 0x76
	s_waitcnt lgkmcnt(1)
	v_mfma_f32_16x16x32_bf16 v[102:105], v[26:29], v[204:207], v[30:33]
	s_waitcnt lgkmcnt(0)
	global_store_dwordx4 v[178:179], v[208:211], off sc1
	global_load_dwordx4 v[38:41], v[108:109], off
	global_load_dwordx4 v[34:37], v[108:109], off offset:1024
	global_load_dwordx4 v[30:33], v[108:109], off offset:2048
	global_load_dwordx4 v[26:29], v[108:109], off offset:3072
	global_load_dwordx2 v[130:131], v[106:107], off
	s_nop 0
	v_cvt_pk_bf16_f32 v116, v98, v99
	v_cvt_pk_bf16_f32 v117, v100, v101
	global_load_dwordx2 v[126:127], v[110:111], off
	s_nop 2
	v_cvt_pk_bf16_f32 v176, v102, v103
	v_cvt_pk_bf16_f32 v177, v104, v105
	global_load_dword v128, v[112:113], off
	ds_write_b64 v129, v[116:117]
	ds_write_b64 v119, v[176:177]
	s_waitcnt lgkmcnt(0)
	s_barrier
	ds_read_b128 v[106:109], v1
	ds_read_b128 v[110:113], v1 offset:1024
	ds_read_b128 v[176:179], v1 offset:2048
	ds_read_b128 v[184:187], v1 offset:3072
	ds_read_b128 v[188:191], v1 offset:4096
	ds_read_b128 v[192:195], v1 offset:5120
	ds_read_b128 v[196:199], v1 offset:6144
	ds_read_b128 v[200:203], v1 offset:7168
	ds_read_b128 v[204:207], v155 offset:16384
	s_waitcnt vmcnt(35)
	s_add_i32 s0, s0, s39
	v_lshlrev_b32_e32 v116, 16, v136
	v_and_b32_e32 v117, 0xffff0000, v136
	v_lshlrev_b32_e32 v136, 16, v137
	v_and_b32_e32 v137, 0xffff0000, v137
	v_lshlrev_b32_e32 v208, 16, v132
	v_and_b32_e32 v209, 0xffff0000, v132
	v_lshlrev_b32_e32 v132, 16, v133
	v_and_b32_e32 v133, 0xffff0000, v133
	v_pk_fma_f32 v[100:101], v[100:101], v[134:135], v[136:137] op_sel_hi:[1,0,1]
	v_pk_fma_f32 v[98:99], v[98:99], v[134:135], v[116:117] op_sel_hi:[1,0,1]
	v_pk_fma_f32 v[104:105], v[104:105], v[134:135], v[132:133] op_sel_hi:[1,0,1]
	v_pk_fma_f32 v[102:103], v[102:103], v[134:135], v[208:209] op_sel_hi:[1,0,1]
	s_waitcnt lgkmcnt(8)
	v_mfma_f32_16x16x32_bf16 v[98:101], v[54:57], v[106:109], v[98:101]
	s_lshl_b32 s0, s0, 2
	s_or_b32 s3, s0, s5
	s_lshl_b32 s0, s3, 16
	s_waitcnt lgkmcnt(7)
	v_mfma_f32_16x16x32_bf16 v[54:57], v[54:57], v[110:113], v[102:105]
	s_add_u32 s46, s62, s0
	s_addc_u32 s47, s63, 0
	s_lshl_b32 s0, s3, 15
	s_waitcnt lgkmcnt(6)
	v_mfma_f32_16x16x32_bf16 v[98:101], v[50:53], v[176:179], v[98:101]
	s_lshl_b32 s3, s3, 9
	v_lshl_add_u64 v[106:107], v[124:125], 0, s[0:1]
	v_lshl_add_u64 v[110:111], v[106:107], 0, s[8:9]
	s_waitcnt lgkmcnt(5)
	v_mfma_f32_16x16x32_bf16 v[50:53], v[50:53], v[184:187], v[54:57]
	s_waitcnt lgkmcnt(4)
	v_mfma_f32_16x16x32_bf16 v[54:57], v[46:49], v[188:191], v[98:101]
	s_waitcnt lgkmcnt(3)
	v_mfma_f32_16x16x32_bf16 v[46:49], v[46:49], v[192:195], v[50:53]
	s_nop 0
	v_lshl_add_u64 v[98:99], s[46:47], 0, v[174:175]
	v_lshl_add_u64 v[108:109], v[98:99], 0, s[6:7]
	s_add_u32 s46, s33, s3
	s_waitcnt lgkmcnt(2)
	v_mfma_f32_16x16x32_bf16 v[98:101], v[42:45], v[196:199], v[54:57]
	s_addc_u32 s47, s36, 0
	v_mov_b64_e32 v[112:113], s[46:47]
	s_min_u32 s0, s45, 0x75
	s_waitcnt lgkmcnt(1)
	v_mfma_f32_16x16x32_bf16 v[102:105], v[42:45], v[200:203], v[46:49]
	s_waitcnt lgkmcnt(0)
	global_store_dwordx4 v[180:181], v[204:207], off sc1
	global_load_dwordx4 v[54:57], v[108:109], off
	global_load_dwordx4 v[50:53], v[108:109], off offset:1024
	global_load_dwordx4 v[46:49], v[108:109], off offset:2048
	global_load_dwordx4 v[42:45], v[108:109], off offset:3072
	global_load_dwordx2 v[136:137], v[106:107], off
	s_nop 0
	v_cvt_pk_bf16_f32 v116, v98, v99
	v_cvt_pk_bf16_f32 v117, v100, v101
	global_load_dwordx2 v[132:133], v[110:111], off
	s_nop 2
	v_cvt_pk_bf16_f32 v176, v102, v103
	v_cvt_pk_bf16_f32 v177, v104, v105
	global_load_dword v134, v[112:113], off
	ds_write_b64 v129, v[116:117] offset:8192
	ds_write_b64 v119, v[176:177] offset:8192
	s_waitcnt lgkmcnt(0)
	s_barrier
	ds_read_b128 v[106:109], v1 offset:8192
	ds_read_b128 v[110:113], v1 offset:9216
	ds_read_b128 v[176:179], v1 offset:10240
	ds_read_b128 v[184:187], v1 offset:11264
	ds_read_b128 v[188:191], v1 offset:12288
	ds_read_b128 v[192:195], v1 offset:13312
	ds_read_b128 v[196:199], v1 offset:14336
	ds_read_b128 v[200:203], v1 offset:15360
	ds_read_b128 v[204:207], v155
	s_waitcnt vmcnt(35)
	s_add_i32 s0, s0, s40
	v_lshlrev_b32_e32 v116, 16, v146
	v_and_b32_e32 v117, 0xffff0000, v146
	v_lshlrev_b32_e32 v146, 16, v147
	v_and_b32_e32 v147, 0xffff0000, v147
	v_lshlrev_b32_e32 v180, 16, v142
	v_and_b32_e32 v181, 0xffff0000, v142
	v_lshlrev_b32_e32 v142, 16, v143
	v_and_b32_e32 v143, 0xffff0000, v143
	v_pk_fma_f32 v[100:101], v[100:101], v[144:145], v[146:147] op_sel_hi:[1,0,1]
	v_pk_fma_f32 v[98:99], v[98:99], v[144:145], v[116:117] op_sel_hi:[1,0,1]
	v_pk_fma_f32 v[104:105], v[104:105], v[144:145], v[142:143] op_sel_hi:[1,0,1]
	v_pk_fma_f32 v[102:103], v[102:103], v[144:145], v[180:181] op_sel_hi:[1,0,1]
	s_waitcnt lgkmcnt(8)
	v_mfma_f32_16x16x32_bf16 v[98:101], v[78:81], v[106:109], v[98:101]
	s_lshl_b32 s0, s0, 2
	s_or_b32 s3, s0, s5
	s_lshl_b32 s0, s3, 16
	s_waitcnt lgkmcnt(7)
	v_mfma_f32_16x16x32_bf16 v[78:81], v[78:81], v[110:113], v[102:105]
	s_add_u32 s46, s62, s0
	s_addc_u32 s47, s63, 0
	s_lshl_b32 s0, s3, 15
	s_waitcnt lgkmcnt(6)
	v_mfma_f32_16x16x32_bf16 v[98:101], v[74:77], v[176:179], v[98:101]
	v_lshl_add_u64 v[102:103], s[46:47], 0, v[174:175]
	v_lshl_add_u64 v[108:109], v[102:103], 0, s[6:7]
	s_lshl_b32 s3, s3, 9
	s_waitcnt lgkmcnt(5)
	v_mfma_f32_16x16x32_bf16 v[74:77], v[74:77], v[184:187], v[78:81]
	v_lshl_add_u64 v[106:107], v[124:125], 0, s[0:1]
	s_add_u32 s46, s33, s3
	v_lshl_add_u64 v[110:111], v[106:107], 0, s[8:9]
	s_waitcnt lgkmcnt(4)
	v_mfma_f32_16x16x32_bf16 v[78:81], v[70:73], v[188:191], v[98:101]
	s_addc_u32 s47, s36, 0
	v_mov_b64_e32 v[112:113], s[46:47]
	s_min_u32 s0, s45, 0x74
	s_waitcnt lgkmcnt(3)
	v_mfma_f32_16x16x32_bf16 v[70:73], v[70:73], v[192:195], v[74:77]
	s_add_i32 s0, s0, s41
	s_lshl_b32 s0, s0, 2
	s_or_b32 s3, s0, s5
	s_waitcnt lgkmcnt(2)
	v_mfma_f32_16x16x32_bf16 v[98:101], v[66:69], v[196:199], v[78:81]
	s_lshl_b32 s0, s3, 16
	s_add_u32 s46, s62, s0
	s_addc_u32 s47, s63, 0
	s_waitcnt lgkmcnt(1)
	v_mfma_f32_16x16x32_bf16 v[102:105], v[66:69], v[200:203], v[70:73]
	s_waitcnt lgkmcnt(0)
	global_store_dwordx4 v[182:183], v[204:207], off sc1
	global_load_dwordx4 v[78:81], v[108:109], off
	global_load_dwordx4 v[74:77], v[108:109], off offset:1024
	global_load_dwordx4 v[70:73], v[108:109], off offset:2048
	global_load_dwordx4 v[66:69], v[108:109], off offset:3072
	global_load_dwordx2 v[146:147], v[106:107], off
	s_nop 0
	v_cvt_pk_bf16_f32 v116, v98, v99
	v_cvt_pk_bf16_f32 v117, v100, v101
	global_load_dwordx2 v[142:143], v[110:111], off
	s_nop 2
	v_cvt_pk_bf16_f32 v176, v102, v103
	v_cvt_pk_bf16_f32 v177, v104, v105
	global_load_dword v144, v[112:113], off
	ds_write_b64 v129, v[116:117] offset:16384
	ds_write_b64 v119, v[176:177] offset:16384
	s_waitcnt lgkmcnt(0)
	s_barrier
	ds_read_b128 v[106:109], v1 offset:16384
	ds_read_b128 v[110:113], v1 offset:17408
	ds_read_b128 v[176:179], v1 offset:18432
	ds_read_b128 v[180:183], v1 offset:19456
	ds_read_b128 v[184:187], v1 offset:20480
	ds_read_b128 v[188:191], v1 offset:21504
	ds_read_b128 v[192:195], v1 offset:22528
	ds_read_b128 v[196:199], v1 offset:23552
	ds_read_b128 v[200:203], v155 offset:8192
	s_waitcnt vmcnt(35)
	s_lshl_b32 s0, s3, 15
	v_lshlrev_b32_e32 v116, 16, v156
	v_and_b32_e32 v117, 0xffff0000, v156
	v_lshlrev_b32_e32 v156, 16, v157
	v_and_b32_e32 v157, 0xffff0000, v157
	v_lshlrev_b32_e32 v204, 16, v152
	v_and_b32_e32 v205, 0xffff0000, v152
	v_lshlrev_b32_e32 v152, 16, v153
	v_and_b32_e32 v153, 0xffff0000, v153
	v_pk_fma_f32 v[100:101], v[100:101], v[154:155], v[156:157] op_sel_hi:[1,0,1]
	v_pk_fma_f32 v[98:99], v[98:99], v[154:155], v[116:117] op_sel_hi:[1,0,1]
	v_pk_fma_f32 v[104:105], v[104:105], v[154:155], v[152:153] op_sel_hi:[1,0,1]
	v_pk_fma_f32 v[102:103], v[102:103], v[154:155], v[204:205] op_sel_hi:[1,0,1]
	s_waitcnt lgkmcnt(8)
	v_mfma_f32_16x16x32_bf16 v[98:101], v[94:97], v[106:109], v[98:101]
	s_lshl_b32 s3, s3, 9
	v_lshl_add_u64 v[106:107], v[124:125], 0, s[0:1]
	s_waitcnt lgkmcnt(7)
	v_mfma_f32_16x16x32_bf16 v[94:97], v[94:97], v[110:113], v[102:105]
	v_lshl_add_u64 v[110:111], v[106:107], 0, s[8:9]
	s_waitcnt lgkmcnt(6)
	v_mfma_f32_16x16x32_bf16 v[98:101], v[90:93], v[176:179], v[98:101]
	v_lshl_add_u64 v[102:103], s[46:47], 0, v[174:175]
	s_add_u32 s46, s33, s3
	v_lshl_add_u64 v[108:109], v[102:103], 0, s[6:7]
	s_waitcnt lgkmcnt(5)
	v_mfma_f32_16x16x32_bf16 v[90:93], v[90:93], v[180:183], v[94:97]
	s_addc_u32 s47, s36, 0
	s_add_u32 s35, s35, 0x180000
	s_addc_u32 s42, s42, 0
	s_waitcnt lgkmcnt(4)
	v_mfma_f32_16x16x32_bf16 v[94:97], v[86:89], v[184:187], v[98:101]
	s_add_u32 s10, s10, 0x3000
	s_addc_u32 s11, s11, 0
	s_add_u32 s43, s43, 0x180000
	s_waitcnt lgkmcnt(3)
	v_mfma_f32_16x16x32_bf16 v[86:89], v[86:89], v[188:191], v[90:93]
	s_addc_u32 s44, s44, 0
	v_mov_b64_e32 v[112:113], s[46:47]
	s_add_u32 s18, s18, 0x3000
	s_waitcnt lgkmcnt(2)
	v_mfma_f32_16x16x32_bf16 v[102:105], v[82:85], v[192:195], v[94:97]
	s_addc_u32 s19, s19, 0
	s_cmpk_lt_u32 s45, 0x78
	s_waitcnt lgkmcnt(1)
	v_mfma_f32_16x16x32_bf16 v[98:101], v[82:85], v[196:199], v[86:89]
	s_waitcnt lgkmcnt(0)
	global_store_dwordx4 v[114:115], v[200:203], off sc1
	global_load_dwordx4 v[94:97], v[108:109], off
	global_load_dwordx4 v[90:93], v[108:109], off offset:1024
	global_load_dwordx4 v[86:89], v[108:109], off offset:2048
	global_load_dwordx4 v[82:85], v[108:109], off offset:3072
	global_load_dwordx2 v[156:157], v[106:107], off
	global_load_dwordx2 v[152:153], v[110:111], off
	global_load_dword v154, v[112:113], off
	s_cbranch_scc1 .LBB0_675
; #define GAS __attribute__((address_space(1)))
; #define LAS __attribute__((address_space(3)))
;     ...
;     asm volatile("s_waitcnt vmcnt(0)" : DN_ALL(p0), DN_ALL(p1), DN_ALL(p2) :: "memory");
;     asm volatile("s_waitcnt vmcnt(0)" : DN_ALL(p3), DN_ALL(p4), DN_ALL(p5) :: "memory");
;     asm volatile("s_waitcnt vmcnt(0)" : DN_ALL(p0), DN_ALL(p1), DN_ALL(p2) :: "memory");
;     DN_STEP(p0, 126, 0, false, MODE); DN_STEP(p1, 127, 1, false, MODE);
;     __syncthreads();
;     if (!(MODE & 2) && ST) { const int unit = (b * NCH + 127) * 4 + h;
;         *(GAS v4u*)(BNB + (size_t)unit * 16384 + (size_t)(((2 * sl + (wave & 1)) * 4 + (wave >> 1)) * 64 + lane) * 8) = *(const LAS v4u*)(lds + 1 * 8192 + (wave * 64 + lane) * 16); }
	s_waitcnt vmcnt(0)
	s_waitcnt vmcnt(0)
	s_nop 0
	v_cvt_pk_bf16_f32 v106, v102, v103
	s_waitcnt vmcnt(0)
	v_cvt_pk_bf16_f32 v107, v104, v105
	s_nop 1
	v_cvt_pk_bf16_f32 v26, v98, v99
	v_cvt_pk_bf16_f32 v27, v100, v101
	ds_write_b64 v129, v[106:107]
	ds_write_b64 v119, v[26:27]
	s_waitcnt lgkmcnt(0)
	s_barrier
	ds_read_b128 v[26:29], v1
	ds_read_b128 v[30:33], v1 offset:1024
	v_lshlrev_b32_e32 v34, 16, v122
	v_and_b32_e32 v35, 0xffff0000, v122
	v_lshlrev_b32_e32 v36, 16, v123
	v_and_b32_e32 v37, 0xffff0000, v123
	v_pk_fma_f32 v[36:37], v[104:105], v[118:119], v[36:37] op_sel_hi:[1,0,1]
	v_pk_fma_f32 v[34:35], v[102:103], v[118:119], v[34:35] op_sel_hi:[1,0,1]
	v_lshlrev_b32_e32 v38, 16, v120
	v_and_b32_e32 v39, 0xffff0000, v120
	v_lshlrev_b32_e32 v40, 16, v121
	v_and_b32_e32 v41, 0xffff0000, v121
	s_waitcnt lgkmcnt(1)
	v_mfma_f32_16x16x32_bf16 v[26:29], v[22:25], v[26:29], v[34:37]
	s_or_b32 s0, s4, s73
	s_lshl_b32 s0, s0, 5
	s_or_b32 s3, s5, s0
	v_pk_fma_f32 v[36:37], v[100:101], v[118:119], v[40:41] op_sel_hi:[1,0,1]
	v_pk_fma_f32 v[34:35], v[98:99], v[118:119], v[38:39] op_sel_hi:[1,0,1]
	s_or_b32 s0, s3, 0x1f8
	s_mov_b32 s1, 0
	s_waitcnt lgkmcnt(0)
	v_mfma_f32_16x16x32_bf16 v[22:25], v[22:25], v[30:33], v[34:37]
	ds_read_b128 v[30:33], v1 offset:2048
	s_nop 1
	ds_read_b128 v[34:37], v1 offset:3072
	s_add_i32 s0, s0, -4
	s_lshl_b64 s[4:5], s[0:1], 15
	s_waitcnt lgkmcnt(1)
	v_mfma_f32_16x16x32_bf16 v[26:29], v[18:21], v[30:33], v[26:29]
	s_add_u32 s4, s64, s4
	s_addc_u32 s5, s65, s5
	s_or_b32 s3, s3, 0x1fc
	s_waitcnt lgkmcnt(0)
	v_mfma_f32_16x16x32_bf16 v[18:21], v[18:21], v[34:37], v[22:25]
	s_nop 2
	ds_read_b128 v[22:25], v1 offset:4096
	ds_read_b128 v[30:33], v1 offset:5120
	s_add_i32 s0, s3, -4
	s_lshl_b64 s[0:1], s[0:1], 15
	s_waitcnt lgkmcnt(1)
	v_mfma_f32_16x16x32_bf16 v[22:25], v[10:13], v[22:25], v[26:29]
	s_add_u32 s0, s64, s0
	s_addc_u32 s1, s65, s1
	s_nop 0
	ds_read_b128 v[26:29], v1 offset:6144
	s_waitcnt lgkmcnt(1)
	v_mfma_f32_16x16x32_bf16 v[10:13], v[10:13], v[30:33], v[18:21]
	v_lshlrev_b64 v[30:31], 4, v[148:149]
	s_nop 1
	ds_read_b128 v[18:21], v1 offset:7168
	s_waitcnt lgkmcnt(1)
	v_mfma_f32_16x16x32_bf16 v[22:25], v[2:5], v[26:29], v[22:25]
	v_or_b32_e32 v26, s37, v145
	v_add_u32_e32 v32, 0, v26
	ds_read_b128 v[26:29], v32 offset:16384
	s_waitcnt lgkmcnt(1)
	v_mfma_f32_16x16x32_bf16 v[2:5], v[2:5], v[18:21], v[10:13]
	s_nop 2
	v_lshl_add_u64 v[10:11], s[4:5], 0, v[30:31]
	s_waitcnt lgkmcnt(0)
	global_store_dwordx4 v[10:11], v[26:29], off sc1
	v_cvt_pk_bf16_f32 v10, v22, v23
	v_cvt_pk_bf16_f32 v11, v24, v25
	ds_write_b64 v129, v[10:11] offset:8192
	v_cvt_pk_bf16_f32 v10, v2, v3
	v_cvt_pk_bf16_f32 v11, v4, v5
	ds_write_b64 v119, v[10:11] offset:8192
	s_waitcnt lgkmcnt(0)
	s_barrier
	ds_read_b128 v[10:13], v1 offset:8192
	ds_read_b128 v[18:21], v1 offset:9216
	v_lshlrev_b32_e32 v26, 16, v150
	v_and_b32_e32 v27, 0xffff0000, v150
	v_lshlrev_b32_e32 v28, 16, v151
	v_and_b32_e32 v29, 0xffff0000, v151
	v_pk_fma_f32 v[24:25], v[138:139], v[24:25], v[28:29] op_sel_hi:[0,1,1]
	v_pk_fma_f32 v[22:23], v[138:139], v[22:23], v[26:27] op_sel_hi:[0,1,1]
	v_lshlrev_b32_e32 v26, 16, v140
	v_and_b32_e32 v27, 0xffff0000, v140
	v_lshlrev_b32_e32 v28, 16, v141
	v_and_b32_e32 v29, 0xffff0000, v141
	v_pk_fma_f32 v[4:5], v[138:139], v[4:5], v[28:29] op_sel_hi:[0,1,1]
	v_pk_fma_f32 v[2:3], v[138:139], v[2:3], v[26:27] op_sel_hi:[0,1,1]
	s_waitcnt lgkmcnt(1)
	v_mfma_f32_16x16x32_bf16 v[10:13], v[62:65], v[10:13], v[22:25]
	s_waitcnt lgkmcnt(0)
	v_mfma_f32_16x16x32_bf16 v[2:5], v[62:65], v[18:21], v[2:5]
	ds_read_b128 v[18:21], v1 offset:10240
	ds_read_b128 v[22:25], v1 offset:11264
	s_waitcnt lgkmcnt(1)
	v_mfma_f32_16x16x32_bf16 v[10:13], v[58:61], v[18:21], v[10:13]
	s_waitcnt lgkmcnt(0)
	v_mfma_f32_16x16x32_bf16 v[2:5], v[58:61], v[22:25], v[2:5]
	ds_read_b128 v[18:21], v1 offset:12288
	ds_read_b128 v[22:25], v1 offset:13312
	s_waitcnt lgkmcnt(1)
	v_mfma_f32_16x16x32_bf16 v[10:13], v[14:17], v[18:21], v[10:13]
	s_waitcnt lgkmcnt(0)
	v_mfma_f32_16x16x32_bf16 v[2:5], v[14:17], v[22:25], v[2:5]
	ds_read_b128 v[14:17], v1 offset:14336
	ds_read_b128 v[18:21], v1 offset:15360
	s_waitcnt lgkmcnt(1)
	v_mfma_f32_16x16x32_bf16 v[10:13], v[6:9], v[14:17], v[10:13]
	s_waitcnt lgkmcnt(0)
	v_mfma_f32_16x16x32_bf16 v[2:5], v[6:9], v[18:21], v[2:5]
	s_nop 5
	ds_read_b128 v[12:15], v32
	s_nop 0
	v_lshl_add_u64 v[2:3], s[0:1], 0, v[30:31]
	s_waitcnt lgkmcnt(0)
	global_store_dwordx4 v[2:3], v[12:15], off sc1
	s_barrier
	ds_read_b128 v[2:5], v32 offset:8192
	s_lshl_b32 s0, s3, 15
	s_add_u32 s0, s64, s0
	s_addc_u32 s1, s65, 0
	v_lshl_add_u64 v[6:7], s[0:1], 0, v[30:31]
	s_waitcnt lgkmcnt(0)
	global_store_dwordx4 v[6:7], v[2:5], off sc1
	s_cmp_lt_i32 s57, 5
	s_cbranch_scc1 .LBB0_890
	s_branch .LBB0_841
